# merged MMA phase pairs (4 barriers per K-tile) in FFN-up, odd in-proj, both out-proj K-loops; all stage DMAs via saddr form
# speedup vs baseline: 1.0021x; 1.0021x over previous
; #define PG8_STAGE(bufoff, gbase, voff) do { _Pragma("unroll") for (int _i = 0; _i < 2; ++_i) \
;         __builtin_amdgcn_global_load_lds((const unsigned*)((const char*)(gbase) + (voff)[_i]), (LAS unsigned*)(lds + (bufoff) + ldsw + _i * 8192), 16, 0, 0); } while (0)
; #define PG8_WAIT_V(n) asm volatile("s_waitcnt vmcnt(" #n ")" ::: "memory")
; #define PG8_BAR __builtin_amdgcn_s_barrier()
; template <class Epi, class Sched>
; __device__ __forceinline__ void gemm_phase(LAS unsigned char* lds, const Gemm g, const Sched& S, const Epi& E) {
;     ...
;     const char* cA = (const char*)g.A + (size_t)cur.pm * tstepA; const char* cB = (const char*)g.Bt + (size_t)cur.pn * tstepB;
;     S.a_ready(cur);
;     PG8_STAGE(PG8_SB(0, 0), cB, voffB); PG8_STAGE(PG8_SA(0, 0), cA, voffA); PG8_STAGE(PG8_SB(0, 1), cB + hstepB, voffB); PG8_STAGE(PG8_SA(0, 1), cA + hstepA, voffA);
;     if (wr == 1) PG8_BAR;
;     PG8_WAIT_V(4); PG8_BAR;
;     PG8_STAGE(PG8_SB(1, 0), cB + kstep, voffB); PG8_STAGE(PG8_SA(1, 0), cA + kstep, voffA); PG8_STAGE(PG8_SB(1, 1), cB + hstepB + kstep, voffB);
;     PG8_WAIT_V(6); PG8_BAR;
.LBB0_345:
	v_readlane_b32 s18, v254, 37
	s_lshl_b32 s0, s0, 5
	v_mov_b32_e32 v139, v3
	v_readlane_b32 s19, v254, 38
	s_and_b32 s39, s0, 0x60
	s_add_i32 m0, s31, 0x18000
	v_lshl_add_u64 v[4:5], v[4:5], 0, s[8:9]
	v_lshl_add_u64 v[14:15], s[18:19], 0, v[138:139]
	v_mov_b32_e32 v135, v3
	s_lshl_b32 s38, s1, 6
	s_lshl_b32 s4, s1, 13
	s_lshl_b32 s5, s39, 7
	s_waitcnt vmcnt(2)
	s_barrier
	global_load_lds_dwordx4 v[4:5], off
	v_lshl_add_u64 v[4:5], v[6:7], 0, s[8:9]
	s_add_i32 m0, s31, 0x1a000
	s_add_i32 s40, s31, 0x8000
	s_add_i32 s41, s31, 0xa000
	v_lshl_add_u64 v[16:17], s[18:19], 0, v[134:135]
	global_load_lds_dwordx4 v[4:5], off
	v_lshl_add_u64 v[4:5], v[14:15], 0, s[8:9]
	s_mov_b32 m0, s40
	s_add_u32 s0, s20, 0x80080
	global_load_lds_dwordx4 v[4:5], off
	v_lshl_add_u64 v[4:5], v[16:17], 0, s[8:9]
	s_mov_b32 m0, s41
	s_addc_u32 s1, s21, 0
	global_load_lds_dwordx4 v[4:5], off
	s_add_i32 m0, s31, 0x1c000
	v_lshl_add_u64 v[4:5], s[0:1], 0, v[136:137]
	global_load_lds_dwordx4 v[4:5], off
	v_lshl_add_u64 v[4:5], s[0:1], 0, v[132:133]
	s_add_i32 m0, s31, 0x1e000
	s_movk_i32 s0, 0x3c0
	global_load_lds_dwordx4 v[4:5], off
	v_and_b32_e32 v4, 48, v1
	v_lshlrev_b32_e32 v5, 6, v1
	v_lshlrev_b32_e32 v1, 2, v1
	v_and_or_b32 v4, v5, s0, v4
	v_and_b32_e32 v1, 32, v1
	v_bitop3_b32 v5, v4, s4, v1 bitop3:0xde
	v_bitop3_b32 v1, s5, v4, v1 bitop3:0xf6
	v_lshlrev_b32_e32 v4, 15, v11
	v_and_b32_e32 v4, 0xffff0000, v4
	v_lshl_add_u32 v4, v10, 12, v4
	v_and_b32_e32 v6, 1, v11
	v_lshl_or_b32 v4, v6, 6, v4
	s_and_b32 s0, s2, 0xffffff00
	v_lshl_add_u32 v140, v12, 1, v4
	v_lshlrev_b32_e32 v4, 15, v2
	s_add_i32 s46, s0, 0
	v_readlane_b32 s4, v252, 0
	v_and_b32_e32 v4, 0xffff0000, v4
	s_waitcnt vmcnt(6)
	s_add_i32 s46, s46, 0x21000
	s_lshl_b32 s0, s39, 1
	v_readlane_b32 s6, v252, 2
	v_lshl_add_u32 v4, v8, 12, v4
	v_and_b32_e32 v2, 1, v2
	v_readlane_b32 s7, v252, 3
	s_add_u32 s47, s6, s0
	v_lshl_or_b32 v2, v2, 6, v4
	v_readlane_b32 s0, v254, 35
	s_addc_u32 s48, s7, 0
	v_mov_b32_e32 v141, v3
	v_lshl_add_u32 v142, v9, 1, v2
	v_mov_b32_e32 v143, v3
	s_mov_b32 s45, 0
	v_add_u32_e32 v149, 0, v5
	v_readlane_b32 s44, v254, 4
	s_mov_b32 s50, s0
	s_mov_b64 s[6:7], s[18:19]
	s_barrier
	v_readlane_b32 s5, v252, 1
	v_readlane_b32 s1, v254, 36
	s_branch .LBB0_347

; #define PG8_STAGE(bufoff, gbase, voff) do { _Pragma("unroll") for (int _i = 0; _i < 2; ++_i) \
;         __builtin_amdgcn_global_load_lds((const unsigned*)((const char*)(gbase) + (voff)[_i]), (LAS unsigned*)(lds + (bufoff) + ldsw + _i * 8192), 16, 0, 0); } while (0)
; #define PG8_LDA(dst, b, h) do { _Pragma("unroll") for (int m = 0; m < 4; ++m) _Pragma("unroll") for (int k = 0; k < 2; ++k) dst[m][k] = *(const LAS bf16x8*)(lds + PG8_SA(b, h) + aoff + m * 2048 + k * 1024); } while (0)
; #define PG8_LDB(dst, b, h) do { _Pragma("unroll") for (int n = 0; n < 2; ++n) _Pragma("unroll") for (int k = 0; k < 2; ++k) dst[n][k] = *(const LAS bf16x8*)(lds + PG8_SB(b, h) + boff + n * 2048 + k * 1024); } while (0)
; #define PG8_MMA(ai, bj, At, Bt) do { __builtin_amdgcn_s_setprio(1); _Pragma("unroll") for (int m = 0; m < 4; ++m) _Pragma("unroll") for (int n = 0; n < 2; ++n) _Pragma("unroll") for (int k = 0; k < 2; ++k) \
;         acc[ai][bj][m][n] = __builtin_amdgcn_mfma_f32_16x16x32_bf16(Bt[n][k], At[m][k], acc[ai][bj][m][n], 0, 0, 0); __builtin_amdgcn_s_setprio(0); } while (0)
; #define PG8_WAIT_V(n) asm volatile("s_waitcnt vmcnt(" #n ")" ::: "memory")
; #define PG8_WAIT_L(n) asm volatile("s_waitcnt lgkmcnt(" #n ")" ::: "memory")
; template <class Epi, class Sched>
; __device__ __forceinline__ void gemm_phase(LAS unsigned char* lds, const Gemm g, const Sched& S, const Epi& E) {
;     ...
;             const bool last = (t == nt - 2);
;             const char* a1 = cA + (size_t)(t + 1) * kstep;
;             const char* a2 = last ? nA : cA + (size_t)(t + 2) * kstep; const char* b2 = last ? nB : cB + (size_t)(t + 2) * kstep;
;             const char* a3 = a2 + kstep; const char* b3 = b2 + kstep;
;             if (last && has_next) S.a_ready(nxt);
;             PG8_LDB(B0, 0, 0); PG8_SCHED; PG8_LDA(At, 0, 0); PG8_STAGE(PG8_SA(1, 1), a1 + hstepA, voffA);
;             PG8_WAIT_L(8); PG8_BAR; PG8_WAIT_L(0); PG8_MMA(0, 0, At, B0); PG8_BAR; PG8_SCHED;
;             PG8_LDB(B1, 0, 1); PG8_STAGE(PG8_SB(0, 0), b2, voffB);
;             PG8_BAR; PG8_WAIT_L(0); PG8_MMA(0, 1, At, B1); PG8_BAR;
;             PG8_LDA(At, 0, 1); PG8_STAGE(PG8_SA(0, 0), a2, voffA);
;             PG8_BAR; PG8_WAIT_L(0); PG8_MMA(1, 0, At, B0); PG8_BAR; PG8_SCHED;
;             PG8_STAGE(PG8_SB(0, 1), b2 + hstepB, voffB);
;             PG8_WAIT_V(6); PG8_BAR; PG8_MMA(1, 1, At, B1); PG8_BAR;
.LBB0_352:
	s_add_u32 s20, s6, 0xfff80080
	s_addc_u32 s21, s7, -1
	s_add_i32 s56, 0, 0x10000
	v_add_u32_e32 v2, s56, v1
	ds_read_b128 v[144:147], v2
	ds_read_b128 v[150:153], v2 offset:1024
	ds_read_b128 v[154:157], v2 offset:2048
	ds_read_b128 v[158:161], v2 offset:3072
	s_cmp_eq_u32 s55, 28
	s_cselect_b32 s25, s15, s21
	s_cselect_b32 s24, s51, s20
	s_cselect_b32 s21, s1, s54
	s_cselect_b32 s20, s52, s53
	s_add_i32 m0, s31, 0xc000
	ds_read_b128 v[162:165], v149
	ds_read_b128 v[166:169], v149 offset:1024
	ds_read_b128 v[170:173], v149 offset:2048
	ds_read_b128 v[174:177], v149 offset:3072
	ds_read_b128 v[178:181], v149 offset:4096
	ds_read_b128 v[182:185], v149 offset:5120
	ds_read_b128 v[186:189], v149 offset:6144
	ds_read_b128 v[190:193], v149 offset:7168
	s_add_i32 s58, 0, 0x14000
	v_add_u32_e32 v2, s58, v1
	ds_read_b128 v[194:197], v2
	ds_read_b128 v[198:201], v2 offset:1024
	ds_read_b128 v[202:205], v2 offset:2048
	ds_read_b128 v[206:209], v2 offset:3072
	s_add_i32 m0, s31, 0xc000
	s_nop 0
	global_load_lds_dwordx4 v140, s[6:7]
	s_add_i32 m0, s31, 0xe000
	s_nop 0
	global_load_lds_dwordx4 v142, s[6:7]
	s_waitcnt lgkmcnt(0)
	s_barrier
	s_setprio 1
	v_mfma_f32_16x16x32_bf16 v[128:131], v[144:147], v[162:165], v[128:131]
	v_mfma_f32_16x16x32_bf16 v[124:127], v[154:157], v[162:165], v[124:127]
	v_mfma_f32_16x16x32_bf16 v[112:115], v[144:147], v[170:173], v[112:115]
	v_mfma_f32_16x16x32_bf16 v[108:111], v[154:157], v[170:173], v[108:111]
	v_mfma_f32_16x16x32_bf16 v[96:99], v[144:147], v[178:181], v[96:99]
	v_mfma_f32_16x16x32_bf16 v[92:95], v[154:157], v[178:181], v[92:95]
	v_mfma_f32_16x16x32_bf16 v[80:83], v[144:147], v[186:189], v[80:83]
	v_mfma_f32_16x16x32_bf16 v[76:79], v[154:157], v[186:189], v[76:79]
	v_mfma_f32_16x16x32_bf16 v[128:131], v[150:153], v[166:169], v[128:131]
	v_mfma_f32_16x16x32_bf16 v[124:127], v[158:161], v[166:169], v[124:127]
	v_mfma_f32_16x16x32_bf16 v[112:115], v[150:153], v[174:177], v[112:115]
	v_mfma_f32_16x16x32_bf16 v[108:111], v[158:161], v[174:177], v[108:111]
	v_mfma_f32_16x16x32_bf16 v[96:99], v[150:153], v[182:185], v[96:99]
	v_mfma_f32_16x16x32_bf16 v[92:95], v[158:161], v[182:185], v[92:95]
	v_mfma_f32_16x16x32_bf16 v[80:83], v[150:153], v[190:193], v[80:83]
	v_mfma_f32_16x16x32_bf16 v[76:79], v[158:161], v[190:193], v[76:79]
	v_mfma_f32_16x16x32_bf16 v[120:123], v[194:197], v[162:165], v[120:123]
	v_mfma_f32_16x16x32_bf16 v[116:119], v[202:205], v[162:165], v[116:119]
	v_mfma_f32_16x16x32_bf16 v[104:107], v[194:197], v[170:173], v[104:107]
	v_mfma_f32_16x16x32_bf16 v[100:103], v[202:205], v[170:173], v[100:103]
	v_mfma_f32_16x16x32_bf16 v[88:91], v[194:197], v[178:181], v[88:91]
	v_mfma_f32_16x16x32_bf16 v[84:87], v[202:205], v[178:181], v[84:87]
	v_mfma_f32_16x16x32_bf16 v[72:75], v[194:197], v[186:189], v[72:75]
	v_mfma_f32_16x16x32_bf16 v[68:71], v[202:205], v[186:189], v[68:71]
	v_mfma_f32_16x16x32_bf16 v[120:123], v[198:201], v[166:169], v[120:123]
	v_mfma_f32_16x16x32_bf16 v[116:119], v[206:209], v[166:169], v[116:119]
	v_mfma_f32_16x16x32_bf16 v[104:107], v[198:201], v[174:177], v[104:107]
	v_mfma_f32_16x16x32_bf16 v[100:103], v[206:209], v[174:177], v[100:103]
	v_mfma_f32_16x16x32_bf16 v[88:91], v[198:201], v[182:185], v[88:91]
	v_mfma_f32_16x16x32_bf16 v[84:87], v[206:209], v[182:185], v[84:87]
	v_mfma_f32_16x16x32_bf16 v[72:75], v[198:201], v[190:193], v[72:75]
	v_mfma_f32_16x16x32_bf16 v[68:71], v[206:209], v[190:193], v[68:71]
	s_setprio 0
	s_barrier
	ds_read_b128 v[162:165], v149 offset:16384
	ds_read_b128 v[166:169], v149 offset:17408
	ds_read_b128 v[170:173], v149 offset:18432
	ds_read_b128 v[174:177], v149 offset:19456
	ds_read_b128 v[178:181], v149 offset:20480
	ds_read_b128 v[182:185], v149 offset:21504
	ds_read_b128 v[186:189], v149 offset:22528
	ds_read_b128 v[190:193], v149 offset:23552
	s_add_i32 s56, s56, s30
	v_lshl_add_u64 v[210:211], s[20:21], 0, v[136:137]
	s_mov_b32 m0, s56
	s_nop 0
	global_load_lds_dwordx4 v[210:211], off
	v_lshl_add_u64 v[212:213], s[20:21], 0, v[132:133]
	s_add_i32 m0, s56, 0x2000
	s_nop 0
	global_load_lds_dwordx4 v[212:213], off
	s_mov_b32 m0, s31
	v_lshl_add_u64 v[216:217], s[24:25], 0, v[138:139]
	s_nop 0
	global_load_lds_dwordx4 v[216:217], off
	v_lshl_add_u64 v[218:219], s[24:25], 0, v[134:135]
	s_mov_b32 m0, s35
	s_nop 0
	global_load_lds_dwordx4 v[218:219], off
	s_add_u32 s56, s20, 0x80000
	s_addc_u32 s57, s21, 0
	s_add_i32 s58, s58, s30
	s_mov_b32 m0, s58
	s_nop 0
	global_load_lds_dwordx4 v136, s[56:57]
	s_add_i32 m0, s58, 0x2000
	s_nop 0
	global_load_lds_dwordx4 v132, s[56:57]
	s_waitcnt lgkmcnt(0)
	s_waitcnt vmcnt(6)
	s_barrier
; #define PG8_STAGE(bufoff, gbase, voff) do { _Pragma("unroll") for (int _i = 0; _i < 2; ++_i) \
;         __builtin_amdgcn_global_load_lds((const unsigned*)((const char*)(gbase) + (voff)[_i]), (LAS unsigned*)(lds + (bufoff) + ldsw + _i * 8192), 16, 0, 0); } while (0)
; #define PG8_LDA(dst, b, h) do { _Pragma("unroll") for (int m = 0; m < 4; ++m) _Pragma("unroll") for (int k = 0; k < 2; ++k) dst[m][k] = *(const LAS bf16x8*)(lds + PG8_SA(b, h) + aoff + m * 2048 + k * 1024); } while (0)
; #define PG8_LDB(dst, b, h) do { _Pragma("unroll") for (int n = 0; n < 2; ++n) _Pragma("unroll") for (int k = 0; k < 2; ++k) dst[n][k] = *(const LAS bf16x8*)(lds + PG8_SB(b, h) + boff + n * 2048 + k * 1024); } while (0)
; #define PG8_MMA(ai, bj, At, Bt) do { __builtin_amdgcn_s_setprio(1); _Pragma("unroll") for (int m = 0; m < 4; ++m) _Pragma("unroll") for (int n = 0; n < 2; ++n) _Pragma("unroll") for (int k = 0; k < 2; ++k) \
;         acc[ai][bj][m][n] = __builtin_amdgcn_mfma_f32_16x16x32_bf16(Bt[n][k], At[m][k], acc[ai][bj][m][n], 0, 0, 0); __builtin_amdgcn_s_setprio(0); } while (0)
; #define PG8_WAIT_V(n) asm volatile("s_waitcnt vmcnt(" #n ")" ::: "memory")
; #define PG8_WAIT_L(n) asm volatile("s_waitcnt lgkmcnt(" #n ")" ::: "memory")
; #define PG8_BAR __builtin_amdgcn_s_barrier()
; #define PG8_SCHED __builtin_amdgcn_sched_barrier(0)
; template <class Epi, class Sched>
; __device__ __forceinline__ void gemm_phase(LAS unsigned char* lds, const Gemm g, const Sched& S, const Epi& E) {
;     ...
;             PG8_BAR; PG8_WAIT_L(0); PG8_MMA(1, 0, At, B0); PG8_BAR; PG8_SCHED;
;             PG8_STAGE(PG8_SB(0, 1), b2 + hstepB, voffB);
;             PG8_WAIT_V(6); PG8_BAR; PG8_MMA(1, 1, At, B1); PG8_BAR;
;             PG8_LDB(B0, 1, 0); PG8_SCHED; PG8_LDA(At, 1, 0); PG8_STAGE(PG8_SA(0, 1), a2 + hstepA, voffA);
;             PG8_WAIT_L(8); PG8_BAR; PG8_WAIT_L(0); PG8_MMA(0, 0, At, B0); PG8_BAR; PG8_SCHED;
;             PG8_LDB(B1, 1, 1); PG8_STAGE(PG8_SB(1, 0), b3, voffB);
;             PG8_BAR; PG8_WAIT_L(0); PG8_MMA(0, 1, At, B1); PG8_BAR;
;             PG8_LDA(At, 1, 1); PG8_STAGE(PG8_SA(1, 0), a3, voffA);
;             PG8_BAR; PG8_WAIT_L(0); PG8_MMA(1, 0, At, B0); PG8_BAR; PG8_SCHED;
	s_setprio 1
	v_mfma_f32_16x16x32_bf16 v[64:67], v[144:147], v[162:165], v[64:67]
	v_mfma_f32_16x16x32_bf16 v[60:63], v[154:157], v[162:165], v[60:63]
	v_mfma_f32_16x16x32_bf16 v[48:51], v[144:147], v[170:173], v[48:51]
	v_mfma_f32_16x16x32_bf16 v[44:47], v[154:157], v[170:173], v[44:47]
	v_mfma_f32_16x16x32_bf16 v[32:35], v[144:147], v[178:181], v[32:35]
	v_mfma_f32_16x16x32_bf16 v[28:31], v[154:157], v[178:181], v[28:31]
	v_mfma_f32_16x16x32_bf16 v[16:19], v[144:147], v[186:189], v[16:19]
	v_mfma_f32_16x16x32_bf16 v[12:15], v[154:157], v[186:189], v[12:15]
	v_mfma_f32_16x16x32_bf16 v[64:67], v[150:153], v[166:169], v[64:67]
	v_mfma_f32_16x16x32_bf16 v[60:63], v[158:161], v[166:169], v[60:63]
	v_mfma_f32_16x16x32_bf16 v[48:51], v[150:153], v[174:177], v[48:51]
	v_mfma_f32_16x16x32_bf16 v[44:47], v[158:161], v[174:177], v[44:47]
	v_mfma_f32_16x16x32_bf16 v[32:35], v[150:153], v[182:185], v[32:35]
	v_mfma_f32_16x16x32_bf16 v[28:31], v[158:161], v[182:185], v[28:31]
	v_mfma_f32_16x16x32_bf16 v[16:19], v[150:153], v[190:193], v[16:19]
	v_mfma_f32_16x16x32_bf16 v[12:15], v[158:161], v[190:193], v[12:15]
	v_mfma_f32_16x16x32_bf16 v[56:59], v[194:197], v[162:165], v[56:59]
	v_mfma_f32_16x16x32_bf16 v[52:55], v[202:205], v[162:165], v[52:55]
	v_mfma_f32_16x16x32_bf16 v[40:43], v[194:197], v[170:173], v[40:43]
	v_mfma_f32_16x16x32_bf16 v[36:39], v[202:205], v[170:173], v[36:39]
	v_mfma_f32_16x16x32_bf16 v[24:27], v[194:197], v[178:181], v[24:27]
	v_mfma_f32_16x16x32_bf16 v[20:23], v[202:205], v[178:181], v[20:23]
	v_mfma_f32_16x16x32_bf16 v[8:11], v[194:197], v[186:189], v[8:11]
	v_mfma_f32_16x16x32_bf16 v[4:7], v[202:205], v[186:189], v[4:7]
	v_mfma_f32_16x16x32_bf16 v[56:59], v[198:201], v[166:169], v[56:59]
	v_mfma_f32_16x16x32_bf16 v[52:55], v[206:209], v[166:169], v[52:55]
	v_mfma_f32_16x16x32_bf16 v[40:43], v[198:201], v[174:177], v[40:43]
	v_mfma_f32_16x16x32_bf16 v[36:39], v[206:209], v[174:177], v[36:39]
	v_mfma_f32_16x16x32_bf16 v[24:27], v[198:201], v[182:185], v[24:27]
	v_mfma_f32_16x16x32_bf16 v[20:23], v[206:209], v[182:185], v[20:23]
	v_mfma_f32_16x16x32_bf16 v[8:11], v[198:201], v[190:193], v[8:11]
	v_mfma_f32_16x16x32_bf16 v[4:7], v[206:209], v[190:193], v[4:7]
	s_setprio 0
	s_add_i32 s56, 0, 0x18000
	v_add_u32_e32 v2, s56, v1
	s_barrier
	ds_read_b128 v[144:147], v2
	ds_read_b128 v[150:153], v2 offset:1024
	ds_read_b128 v[154:157], v2 offset:2048
	ds_read_b128 v[158:161], v2 offset:3072
	s_add_u32 s24, s24, 0x80000
	s_addc_u32 s25, s25, 0
	s_mov_b32 m0, s36
	ds_read_b128 v[162:165], v149 offset:32768
	ds_read_b128 v[166:169], v149 offset:33792
	ds_read_b128 v[170:173], v149 offset:34816
	ds_read_b128 v[174:177], v149 offset:35840
	ds_read_b128 v[178:181], v149 offset:36864
	ds_read_b128 v[182:185], v149 offset:37888
	ds_read_b128 v[186:189], v149 offset:38912
	ds_read_b128 v[190:193], v149 offset:39936
	global_load_lds_dwordx4 v138, s[24:25]
	s_mov_b32 m0, s37
	s_nop 0
	global_load_lds_dwordx4 v134, s[24:25]
	s_add_i32 s24, 0, 0x1c000
	v_add_u32_e32 v2, s24, v1
	ds_read_b128 v[194:197], v2
	ds_read_b128 v[198:201], v2 offset:1024
	ds_read_b128 v[202:205], v2 offset:2048
	ds_read_b128 v[206:209], v2 offset:3072
	s_waitcnt lgkmcnt(0)
	s_barrier
	s_setprio 1
	v_mfma_f32_16x16x32_bf16 v[128:131], v[144:147], v[162:165], v[128:131]
	v_mfma_f32_16x16x32_bf16 v[124:127], v[154:157], v[162:165], v[124:127]
	v_mfma_f32_16x16x32_bf16 v[112:115], v[144:147], v[170:173], v[112:115]
	v_mfma_f32_16x16x32_bf16 v[108:111], v[154:157], v[170:173], v[108:111]
	v_mfma_f32_16x16x32_bf16 v[96:99], v[144:147], v[178:181], v[96:99]
	v_mfma_f32_16x16x32_bf16 v[92:95], v[154:157], v[178:181], v[92:95]
	v_mfma_f32_16x16x32_bf16 v[80:83], v[144:147], v[186:189], v[80:83]
	v_mfma_f32_16x16x32_bf16 v[76:79], v[154:157], v[186:189], v[76:79]
	v_mfma_f32_16x16x32_bf16 v[128:131], v[150:153], v[166:169], v[128:131]
	v_mfma_f32_16x16x32_bf16 v[124:127], v[158:161], v[166:169], v[124:127]
	v_mfma_f32_16x16x32_bf16 v[112:115], v[150:153], v[174:177], v[112:115]
	v_mfma_f32_16x16x32_bf16 v[108:111], v[158:161], v[174:177], v[108:111]
	v_mfma_f32_16x16x32_bf16 v[96:99], v[150:153], v[182:185], v[96:99]
	v_mfma_f32_16x16x32_bf16 v[92:95], v[158:161], v[182:185], v[92:95]
	v_mfma_f32_16x16x32_bf16 v[80:83], v[150:153], v[190:193], v[80:83]
	v_mfma_f32_16x16x32_bf16 v[76:79], v[158:161], v[190:193], v[76:79]
	v_mfma_f32_16x16x32_bf16 v[120:123], v[194:197], v[162:165], v[120:123]
	v_mfma_f32_16x16x32_bf16 v[116:119], v[202:205], v[162:165], v[116:119]
	v_mfma_f32_16x16x32_bf16 v[104:107], v[194:197], v[170:173], v[104:107]
	v_mfma_f32_16x16x32_bf16 v[100:103], v[202:205], v[170:173], v[100:103]
	v_mfma_f32_16x16x32_bf16 v[88:91], v[194:197], v[178:181], v[88:91]
	v_mfma_f32_16x16x32_bf16 v[84:87], v[202:205], v[178:181], v[84:87]
	v_mfma_f32_16x16x32_bf16 v[72:75], v[194:197], v[186:189], v[72:75]
	v_mfma_f32_16x16x32_bf16 v[68:71], v[202:205], v[186:189], v[68:71]
	v_mfma_f32_16x16x32_bf16 v[120:123], v[198:201], v[166:169], v[120:123]
	v_mfma_f32_16x16x32_bf16 v[116:119], v[206:209], v[166:169], v[116:119]
	v_mfma_f32_16x16x32_bf16 v[104:107], v[198:201], v[174:177], v[104:107]
	v_mfma_f32_16x16x32_bf16 v[100:103], v[206:209], v[174:177], v[100:103]
	v_mfma_f32_16x16x32_bf16 v[88:91], v[198:201], v[182:185], v[88:91]
	v_mfma_f32_16x16x32_bf16 v[84:87], v[206:209], v[182:185], v[84:87]
	v_mfma_f32_16x16x32_bf16 v[72:75], v[198:201], v[190:193], v[72:75]
	v_mfma_f32_16x16x32_bf16 v[68:71], v[206:209], v[190:193], v[68:71]
	s_setprio 0
	s_barrier
; __device__ __forceinline__ unsigned cvt_pk_bf16(float lo, float hi) { const f32x2 v = {lo, hi}; const bf16v2_ r = __builtin_convertvector(v, bf16v2_); return __builtin_bit_cast(unsigned, r); }
; __device__ __forceinline__ int opaque_tid() { int t = threadIdx.x; asm volatile("" : "+v"(t)); return t; }
; #define PG8_STAGE(bufoff, gbase, voff) do { _Pragma("unroll") for (int _i = 0; _i < 2; ++_i) \
;         __builtin_amdgcn_global_load_lds((const unsigned*)((const char*)(gbase) + (voff)[_i]), (LAS unsigned*)(lds + (bufoff) + ldsw + _i * 8192), 16, 0, 0); } while (0)
; #define PG8_WAIT_V(n) asm volatile("s_waitcnt vmcnt(" #n ")" ::: "memory")
; #define PG8_WAIT_L(n) asm volatile("s_waitcnt lgkmcnt(" #n ")" ::: "memory")
; #define PG8_BAR __builtin_amdgcn_s_barrier()
; template <class Epi, class Sched>
; __device__ __forceinline__ void gemm_phase(LAS unsigned char* lds, const Gemm g, const Sched& S, const Epi& E) {
;     ...
;             PG8_LDA(At, 1, 1); PG8_STAGE(PG8_SA(1, 0), a3, voffA);
;             PG8_BAR; PG8_WAIT_L(0); PG8_MMA(1, 0, At, B0); PG8_BAR; PG8_SCHED;
;             PG8_STAGE(PG8_SB(1, 1), b3 + hstepB, voffB);
;             PG8_WAIT_V(6); PG8_BAR; PG8_MMA(1, 1, At, B1); PG8_BAR;
;     __device__ __forceinline__ void operator()(const f32x4 (&acc)[2][2][4][2], const Unit& u, int wr, int wc, int ui, int) const {
;         const int ol_ = opaque_tid() & 63, fr = ol_ & 15, fq = ol_ >> 4;
;         const int row0 = u.pm * BM + wr * 64 + fr, col0 = u.pn * BM + wc * 32 + 8 * fq;
;         const bool cmp = (u.pn == 8 || u.pn == 9);
;         bf16_t* cb = (u.pn == 8) ? kcmp : vcmp;
;         float r_[2][4];
;         rs_read(r_, ui, wr, fr);
; #pragma unroll
;         for (int ai = 0; ai < 2; ++ai)
; #pragma unroll
;             for (int m = 0; m < 4; ++m) { const int row = row0 + ai * HALF + m * 16; const float r = r_[ai][m];
; #pragma unroll
;                 for (int bj = 0; bj < 2; ++bj) { const f32x4 v0 = acc[ai][bj][m][0] * r, v1 = acc[ai][bj][m][1] * r;
;                     u32x4 w; w.x = cvt_pk_bf16(v0[0], v0[1]); w.y = cvt_pk_bf16(v0[2], v0[3]); w.z = cvt_pk_bf16(v1[0], v1[1]); w.w = cvt_pk_bf16(v1[2], v1[3]);
;                     bf16_t* p = cmp ? cb + ((size_t)((row / T) * 2 + bj) * T + (row % T)) * 128 + wc * 32 + 8 * fq
;                                     : O + (size_t)row * ldc + col0 + bj * HALF;
;                     *(u32x4*)p = w; } }
	ds_read_b128 v[162:165], v149 offset:49152
	ds_read_b128 v[166:169], v149 offset:50176
	ds_read_b128 v[170:173], v149 offset:51200
	ds_read_b128 v[174:177], v149 offset:52224
	ds_read_b128 v[178:181], v149 offset:53248
	ds_read_b128 v[182:185], v149 offset:54272
	ds_read_b128 v[186:189], v149 offset:55296
	ds_read_b128 v[190:193], v149 offset:56320
	s_add_i32 s25, s56, s30
	v_lshl_add_u64 v[210:211], v[210:211], 0, s[8:9]
	s_mov_b32 m0, s25
	s_nop 0
	global_load_lds_dwordx4 v[210:211], off
	v_lshl_add_u64 v[210:211], v[212:213], 0, s[8:9]
	s_add_i32 m0, s25, 0x2000
	s_nop 0
	global_load_lds_dwordx4 v[210:211], off
	s_mov_b32 m0, s40
	v_lshl_add_u64 v[210:211], v[216:217], 0, s[8:9]
	s_nop 0
	global_load_lds_dwordx4 v[210:211], off
	v_lshl_add_u64 v[210:211], v[218:219], 0, s[8:9]
	s_mov_b32 m0, s41
	s_nop 0
	global_load_lds_dwordx4 v[210:211], off
	s_add_u32 s20, s20, 0x80080
	s_addc_u32 s21, s21, 0
	s_add_i32 s24, s24, s30
	s_mov_b32 m0, s24
	s_nop 0
	global_load_lds_dwordx4 v136, s[20:21]
	s_add_i32 m0, s24, 0x2000
	s_nop 0
	global_load_lds_dwordx4 v132, s[20:21]
	s_waitcnt lgkmcnt(0)
	s_waitcnt vmcnt(6)
	s_barrier
	s_setprio 1
	v_mfma_f32_16x16x32_bf16 v[64:67], v[144:147], v[162:165], v[64:67]
	v_mfma_f32_16x16x32_bf16 v[60:63], v[154:157], v[162:165], v[60:63]
	v_mfma_f32_16x16x32_bf16 v[48:51], v[144:147], v[170:173], v[48:51]
	v_mfma_f32_16x16x32_bf16 v[44:47], v[154:157], v[170:173], v[44:47]
	v_mfma_f32_16x16x32_bf16 v[32:35], v[144:147], v[178:181], v[32:35]
	v_mfma_f32_16x16x32_bf16 v[28:31], v[154:157], v[178:181], v[28:31]
	v_mfma_f32_16x16x32_bf16 v[16:19], v[144:147], v[186:189], v[16:19]
	v_mfma_f32_16x16x32_bf16 v[12:15], v[154:157], v[186:189], v[12:15]
	v_mfma_f32_16x16x32_bf16 v[64:67], v[150:153], v[166:169], v[64:67]
	v_mfma_f32_16x16x32_bf16 v[60:63], v[158:161], v[166:169], v[60:63]
	v_mfma_f32_16x16x32_bf16 v[48:51], v[150:153], v[174:177], v[48:51]
	v_mfma_f32_16x16x32_bf16 v[44:47], v[158:161], v[174:177], v[44:47]
	v_mfma_f32_16x16x32_bf16 v[32:35], v[150:153], v[182:185], v[32:35]
	v_mfma_f32_16x16x32_bf16 v[28:31], v[158:161], v[182:185], v[28:31]
	v_mfma_f32_16x16x32_bf16 v[16:19], v[150:153], v[190:193], v[16:19]
	v_mfma_f32_16x16x32_bf16 v[12:15], v[158:161], v[190:193], v[12:15]
	v_mfma_f32_16x16x32_bf16 v[56:59], v[194:197], v[162:165], v[56:59]
	v_mfma_f32_16x16x32_bf16 v[52:55], v[202:205], v[162:165], v[52:55]
	v_mfma_f32_16x16x32_bf16 v[40:43], v[194:197], v[170:173], v[40:43]
	v_mfma_f32_16x16x32_bf16 v[36:39], v[202:205], v[170:173], v[36:39]
	v_mfma_f32_16x16x32_bf16 v[24:27], v[194:197], v[178:181], v[24:27]
	v_mfma_f32_16x16x32_bf16 v[20:23], v[202:205], v[178:181], v[20:23]
	v_mfma_f32_16x16x32_bf16 v[8:11], v[194:197], v[186:189], v[8:11]
	v_mfma_f32_16x16x32_bf16 v[4:7], v[202:205], v[186:189], v[4:7]
	v_mfma_f32_16x16x32_bf16 v[56:59], v[198:201], v[166:169], v[56:59]
	v_mfma_f32_16x16x32_bf16 v[52:55], v[206:209], v[166:169], v[52:55]
	v_mfma_f32_16x16x32_bf16 v[40:43], v[198:201], v[174:177], v[40:43]
	v_mfma_f32_16x16x32_bf16 v[36:39], v[206:209], v[174:177], v[36:39]
	v_mfma_f32_16x16x32_bf16 v[24:27], v[198:201], v[182:185], v[24:27]
	v_mfma_f32_16x16x32_bf16 v[20:23], v[206:209], v[182:185], v[20:23]
	v_mfma_f32_16x16x32_bf16 v[8:11], v[198:201], v[190:193], v[8:11]
	v_mfma_f32_16x16x32_bf16 v[4:7], v[206:209], v[190:193], v[4:7]
	s_setprio 0
	s_add_i32 s55, s55, 2
	s_add_u32 s6, s6, 0x100
	s_addc_u32 s7, s7, 0
	s_add_u32 s53, s53, 0x100
	s_addc_u32 s54, s54, 0
	s_cmp_gt_u32 s55, 29
	s_barrier
	s_cbranch_scc0 .LBB0_352
	s_lshl_b32 s1, s50, 8
	s_lshl_b32 s6, s44, 8
	s_add_i32 s1, s1, s38
	s_or_b32 s6, s6, s39
	s_cmp_eq_u32 s44, 8
	s_mov_b32 s7, 0x3bcb0000
	s_cselect_b32 s15, s7, 0x3ccb4000
	s_lshl_b32 s7, s45, 10
	v_mov_b32_e32 v2, v0
	s_and_b32 s7, s7, 0x400
	s_add_i32 s7, s46, s7
	v_and_b32_e32 v144, 15, v2
	v_or_b32_e32 v148, s1, v144
	v_lshl_add_u32 v144, v144, 2, s7
	v_lshrrev_b32_e32 v2, 1, v2
	ds_read2_b32 v[164:165], v144 offset1:16
	ds_read2_b32 v[160:161], v144 offset0:32 offset1:48
	ds_read2_b32 v[156:157], v144 offset0:128 offset1:144
	ds_read2_b32 v[152:153], v144 offset0:160 offset1:176
	v_and_b32_e32 v2, 24, v2
	v_or_b32_e32 v146, s6, v2
	s_and_b32 s6, s44, -2
	s_cmp_lg_u32 s6, 8
	s_cselect_b64 s[6:7], -1, 0
	s_add_u32 s24, s47, s15
	s_waitcnt lgkmcnt(0)
	v_mov_b32_e32 v162, v165
	v_mov_b32_e32 v158, v161
	v_mov_b32_e32 v154, v157
	v_mov_b32_e32 v144, v153
	v_ashrrev_i32_e32 v147, 31, v146
	s_addc_u32 s25, s48, 0
	s_mov_b64 s[20:21], -1
	s_and_b64 vcc, exec, s[6:7]
	s_cbranch_vccz .LBB0_355
	v_mov_b64_e32 v[150:151], s[92:93]
	s_movk_i32 s15, 0x3600
	v_mad_i64_i32 v[150:151], s[20:21], v148, s15, v[150:151]
	v_lshl_add_u64 v[170:171], v[146:147], 1, v[150:151]
	s_mov_b64 s[20:21], 0

; #define PG8_STAGE(bufoff, gbase, voff) do { _Pragma("unroll") for (int _i = 0; _i < 2; ++_i) \
;         __builtin_amdgcn_global_load_lds((const unsigned*)((const char*)(gbase) + (voff)[_i]), (LAS unsigned*)(lds + (bufoff) + ldsw + _i * 8192), 16, 0, 0); } while (0)
; #define PG8_WAIT_V(n) asm volatile("s_waitcnt vmcnt(" #n ")" ::: "memory")
; #define PG8_BAR __builtin_amdgcn_s_barrier()
; template <class Epi, class Sched>
; __device__ __forceinline__ void gemm_phase(LAS unsigned char* lds, const Gemm g, const Sched& S, const Epi& E) {
;     ...
;     const char* cA = (const char*)g.A + (size_t)cur.pm * tstepA; const char* cB = (const char*)g.Bt + (size_t)cur.pn * tstepB;
;     S.a_ready(cur);
;     PG8_STAGE(PG8_SB(0, 0), cB, voffB); PG8_STAGE(PG8_SA(0, 0), cA, voffA); PG8_STAGE(PG8_SB(0, 1), cB + hstepB, voffB); PG8_STAGE(PG8_SA(0, 1), cA + hstepA, voffA);
;     if (wr == 1) PG8_BAR;
;     PG8_WAIT_V(4); PG8_BAR;
;     PG8_STAGE(PG8_SB(1, 0), cB + kstep, voffB); PG8_STAGE(PG8_SA(1, 0), cA + kstep, voffA); PG8_STAGE(PG8_SB(1, 1), cB + hstepB + kstep, voffB);
;     PG8_WAIT_V(6); PG8_BAR;
.LBB0_958:
	v_lshl_add_u64 v[10:11], s[20:21], 0, v[2:3]
	v_mov_b32_e32 v193, v3
	v_readlane_b32 s6, v254, 5
	s_lshl_b32 s0, s0, 5
	v_lshl_add_u64 v[12:13], s[20:21], 0, v[192:193]
	v_mov_b32_e32 v197, v3
	v_readlane_b32 s7, v254, 6
	v_and_b32_e32 v18, 48, v1
	v_lshlrev_b32_e32 v19, 6, v1
	s_movk_i32 s4, 0x3c0
	v_lshlrev_b32_e32 v1, 2, v1
	s_and_b32 s39, s0, 0x60
	s_add_i32 m0, s31, 0x18000
	v_lshl_add_u64 v[10:11], v[10:11], 0, s[8:9]
	v_lshl_add_u64 v[14:15], s[6:7], 0, v[196:197]
	v_mov_b32_e32 v195, v3
	s_lshl_b32 s38, s1, 6
	s_lshl_b32 s1, s1, 13
	v_and_or_b32 v18, v19, s4, v18
	v_and_b32_e32 v1, 32, v1
	s_lshl_b32 s0, s39, 7
	s_waitcnt vmcnt(2)
	s_barrier
	global_load_lds_dwordx4 v[10:11], off
	v_lshl_add_u64 v[10:11], v[12:13], 0, s[8:9]
	s_add_i32 m0, s31, 0x1a000
	s_add_i32 s40, s31, 0x8000
	s_add_i32 s41, s31, 0xa000
	v_lshl_add_u64 v[16:17], s[6:7], 0, v[194:195]
	v_bitop3_b32 v19, v18, s1, v1 bitop3:0xde
	v_bitop3_b32 v1, s0, v18, v1 bitop3:0xf6
	global_load_lds_dwordx4 v[10:11], off
	v_lshl_add_u64 v[10:11], v[14:15], 0, s[8:9]
	s_mov_b32 m0, s40
	s_add_u32 s0, s20, 0x80080
	global_load_lds_dwordx4 v[10:11], off
	v_lshl_add_u64 v[10:11], v[16:17], 0, s[8:9]
	s_mov_b32 m0, s41
	s_addc_u32 s1, s21, 0
	global_load_lds_dwordx4 v[10:11], off
	s_add_i32 m0, s31, 0x1c000
	v_lshl_add_u64 v[10:11], s[0:1], 0, v[2:3]
	global_load_lds_dwordx4 v[10:11], off
	v_lshl_add_u64 v[10:11], s[0:1], 0, v[192:193]
	s_add_i32 m0, s31, 0x1e000
	v_readlane_b32 s0, v254, 27
	global_load_lds_dwordx4 v[10:11], off
	v_lshlrev_b32_e32 v10, 15, v8
	v_and_b32_e32 v10, 0xffff0000, v10
	v_lshl_add_u32 v7, v7, 12, v10
	v_and_b32_e32 v8, 1, v8
	v_lshl_or_b32 v7, v8, 6, v7
	v_lshl_add_u32 v198, v9, 1, v7
	v_lshlrev_b32_e32 v7, 15, v4
	v_and_b32_e32 v7, 0xffff0000, v7
	s_waitcnt vmcnt(6)
	v_lshl_add_u32 v5, v5, 12, v7
	v_and_b32_e32 v4, 1, v4
	v_lshl_or_b32 v4, v4, 6, v5
	v_mov_b32_e32 v199, v3
	v_lshl_add_u32 v200, v6, 1, v4
	v_mov_b32_e32 v201, v3
	s_mov_b32 s44, 0
	v_add_u32_e32 v224, 0, v19
	v_readlane_b32 s45, v254, 1
	s_mov_b32 s46, s0
	s_barrier
	v_readlane_b32 s1, v254, 28

; #define PG8_STAGE(bufoff, gbase, voff) do { _Pragma("unroll") for (int _i = 0; _i < 2; ++_i) \
;         __builtin_amdgcn_global_load_lds((const unsigned*)((const char*)(gbase) + (voff)[_i]), (LAS unsigned*)(lds + (bufoff) + ldsw + _i * 8192), 16, 0, 0); } while (0)
; #define PG8_LDA(dst, b, h) do { _Pragma("unroll") for (int m = 0; m < 4; ++m) _Pragma("unroll") for (int k = 0; k < 2; ++k) dst[m][k] = *(const LAS bf16x8*)(lds + PG8_SA(b, h) + aoff + m * 2048 + k * 1024); } while (0)
; #define PG8_LDB(dst, b, h) do { _Pragma("unroll") for (int n = 0; n < 2; ++n) _Pragma("unroll") for (int k = 0; k < 2; ++k) dst[n][k] = *(const LAS bf16x8*)(lds + PG8_SB(b, h) + boff + n * 2048 + k * 1024); } while (0)
; #define PG8_MMA(ai, bj, At, Bt) do { __builtin_amdgcn_s_setprio(1); _Pragma("unroll") for (int m = 0; m < 4; ++m) _Pragma("unroll") for (int n = 0; n < 2; ++n) _Pragma("unroll") for (int k = 0; k < 2; ++k) \
;         acc[ai][bj][m][n] = __builtin_amdgcn_mfma_f32_16x16x32_bf16(Bt[n][k], At[m][k], acc[ai][bj][m][n], 0, 0, 0); __builtin_amdgcn_s_setprio(0); } while (0)
; #define PG8_WAIT_V(n) asm volatile("s_waitcnt vmcnt(" #n ")" ::: "memory")
; #define PG8_WAIT_L(n) asm volatile("s_waitcnt lgkmcnt(" #n ")" ::: "memory")
; template <class Epi, class Sched>
; __device__ __forceinline__ void gemm_phase(LAS unsigned char* lds, const Gemm g, const Sched& S, const Epi& E) {
;     ...
;             const bool last = (t == nt - 2);
;             const char* a1 = cA + (size_t)(t + 1) * kstep;
;             const char* a2 = last ? nA : cA + (size_t)(t + 2) * kstep; const char* b2 = last ? nB : cB + (size_t)(t + 2) * kstep;
;             const char* a3 = a2 + kstep; const char* b3 = b2 + kstep;
;             if (last && has_next) S.a_ready(nxt);
;             PG8_LDB(B0, 0, 0); PG8_SCHED; PG8_LDA(At, 0, 0); PG8_STAGE(PG8_SA(1, 1), a1 + hstepA, voffA);
;             PG8_WAIT_L(8); PG8_BAR; PG8_WAIT_L(0); PG8_MMA(0, 0, At, B0); PG8_BAR; PG8_SCHED;
;             PG8_LDB(B1, 0, 1); PG8_STAGE(PG8_SB(0, 0), b2, voffB);
;             PG8_BAR; PG8_WAIT_L(0); PG8_MMA(0, 1, At, B1); PG8_BAR;
;             PG8_LDA(At, 0, 1); PG8_STAGE(PG8_SA(0, 0), a2, voffA);
;             PG8_BAR; PG8_WAIT_L(0); PG8_MMA(1, 0, At, B0); PG8_BAR; PG8_SCHED;
;             PG8_STAGE(PG8_SB(0, 1), b2 + hstepB, voffB);
;             PG8_WAIT_V(6); PG8_BAR; PG8_MMA(1, 1, At, B1); PG8_BAR;
.LBB0_966:
	s_add_u32 s20, s6, 0xfff80080
	s_addc_u32 s21, s7, -1
	s_add_i32 s52, 0, 0x10000
	v_add_u32_e32 v144, s52, v1
	ds_read_b128 v[132:135], v144
	ds_read_b128 v[136:139], v144 offset:1024
	ds_read_b128 v[140:143], v144 offset:2048
	ds_read_b128 v[144:147], v144 offset:3072
	s_cmp_eq_u32 s51, 28
	s_cselect_b32 s25, s15, s21
	s_cselect_b32 s24, s47, s20
	s_cselect_b32 s21, s1, s50
	s_cselect_b32 s20, s48, s49
	s_add_i32 m0, s31, 0xc000
	ds_read_b128 v[148:151], v224
	ds_read_b128 v[152:155], v224 offset:1024
	ds_read_b128 v[156:159], v224 offset:2048
	ds_read_b128 v[160:163], v224 offset:3072
	ds_read_b128 v[164:167], v224 offset:4096
	ds_read_b128 v[168:171], v224 offset:5120
	ds_read_b128 v[172:175], v224 offset:6144
	ds_read_b128 v[176:179], v224 offset:7168
	s_add_i32 s54, 0, 0x14000
	v_add_u32_e32 v202, s54, v1
	ds_read_b128 v[180:183], v202
	ds_read_b128 v[184:187], v202 offset:1024
	ds_read_b128 v[188:191], v202 offset:2048
	ds_read_b128 v[202:205], v202 offset:3072
	s_add_i32 m0, s31, 0xc000
	s_nop 0
	global_load_lds_dwordx4 v198, s[6:7]
	s_add_i32 m0, s31, 0xe000
	s_nop 0
	global_load_lds_dwordx4 v200, s[6:7]
	s_waitcnt lgkmcnt(0)
	s_barrier
	s_setprio 1
	v_mfma_f32_16x16x32_bf16 v[128:131], v[132:135], v[148:151], v[128:131]
	v_mfma_f32_16x16x32_bf16 v[124:127], v[140:143], v[148:151], v[124:127]
	v_mfma_f32_16x16x32_bf16 v[112:115], v[132:135], v[156:159], v[112:115]
	v_mfma_f32_16x16x32_bf16 v[108:111], v[140:143], v[156:159], v[108:111]
	v_mfma_f32_16x16x32_bf16 v[100:103], v[132:135], v[164:167], v[100:103]
	v_mfma_f32_16x16x32_bf16 v[92:95], v[140:143], v[164:167], v[92:95]
	v_mfma_f32_16x16x32_bf16 v[84:87], v[132:135], v[172:175], v[84:87]
	v_mfma_f32_16x16x32_bf16 v[76:79], v[140:143], v[172:175], v[76:79]
	v_mfma_f32_16x16x32_bf16 v[128:131], v[136:139], v[152:155], v[128:131]
	v_mfma_f32_16x16x32_bf16 v[124:127], v[144:147], v[152:155], v[124:127]
	v_mfma_f32_16x16x32_bf16 v[112:115], v[136:139], v[160:163], v[112:115]
	v_mfma_f32_16x16x32_bf16 v[108:111], v[144:147], v[160:163], v[108:111]
	v_mfma_f32_16x16x32_bf16 v[100:103], v[136:139], v[168:171], v[100:103]
	v_mfma_f32_16x16x32_bf16 v[92:95], v[144:147], v[168:171], v[92:95]
	v_mfma_f32_16x16x32_bf16 v[84:87], v[136:139], v[176:179], v[84:87]
	v_mfma_f32_16x16x32_bf16 v[76:79], v[144:147], v[176:179], v[76:79]
	v_mfma_f32_16x16x32_bf16 v[120:123], v[180:183], v[148:151], v[120:123]
	v_mfma_f32_16x16x32_bf16 v[116:119], v[188:191], v[148:151], v[116:119]
	v_mfma_f32_16x16x32_bf16 v[104:107], v[180:183], v[156:159], v[104:107]
	v_mfma_f32_16x16x32_bf16 v[96:99], v[188:191], v[156:159], v[96:99]
	v_mfma_f32_16x16x32_bf16 v[88:91], v[180:183], v[164:167], v[88:91]
	v_mfma_f32_16x16x32_bf16 v[80:83], v[188:191], v[164:167], v[80:83]
	v_mfma_f32_16x16x32_bf16 v[72:75], v[180:183], v[172:175], v[72:75]
	v_mfma_f32_16x16x32_bf16 v[68:71], v[188:191], v[172:175], v[68:71]
	v_mfma_f32_16x16x32_bf16 v[120:123], v[184:187], v[152:155], v[120:123]
	v_mfma_f32_16x16x32_bf16 v[116:119], v[202:205], v[152:155], v[116:119]
	v_mfma_f32_16x16x32_bf16 v[104:107], v[184:187], v[160:163], v[104:107]
	v_mfma_f32_16x16x32_bf16 v[96:99], v[202:205], v[160:163], v[96:99]
	v_mfma_f32_16x16x32_bf16 v[88:91], v[184:187], v[168:171], v[88:91]
	v_mfma_f32_16x16x32_bf16 v[80:83], v[202:205], v[168:171], v[80:83]
	v_mfma_f32_16x16x32_bf16 v[72:75], v[184:187], v[176:179], v[72:75]
	v_mfma_f32_16x16x32_bf16 v[68:71], v[202:205], v[176:179], v[68:71]
	s_setprio 0
	s_barrier
	ds_read_b128 v[148:151], v224 offset:16384
	ds_read_b128 v[152:155], v224 offset:17408
	ds_read_b128 v[156:159], v224 offset:18432
	ds_read_b128 v[160:163], v224 offset:19456
	ds_read_b128 v[164:167], v224 offset:20480
	ds_read_b128 v[168:171], v224 offset:21504
	ds_read_b128 v[172:175], v224 offset:22528
	ds_read_b128 v[176:179], v224 offset:23552
	s_add_i32 s52, s52, s30
	v_lshl_add_u64 v[206:207], s[20:21], 0, v[2:3]
	s_mov_b32 m0, s52
	s_nop 0
	global_load_lds_dwordx4 v[206:207], off
	v_lshl_add_u64 v[208:209], s[20:21], 0, v[192:193]
	s_add_i32 m0, s52, 0x2000
	s_nop 0
	global_load_lds_dwordx4 v[208:209], off
	s_mov_b32 m0, s31
	v_lshl_add_u64 v[210:211], s[24:25], 0, v[196:197]
	s_nop 0
	global_load_lds_dwordx4 v[210:211], off
	v_lshl_add_u64 v[212:213], s[24:25], 0, v[194:195]
	s_mov_b32 m0, s35
	s_nop 0
	global_load_lds_dwordx4 v[212:213], off
	s_add_u32 s52, s20, 0x80000
	s_addc_u32 s53, s21, 0
	s_add_i32 s54, s54, s30
	s_mov_b32 m0, s54
	s_nop 0
	global_load_lds_dwordx4 v2, s[52:53]
	s_add_i32 m0, s54, 0x2000
	s_nop 0
	global_load_lds_dwordx4 v192, s[52:53]
	s_waitcnt lgkmcnt(0)
	s_waitcnt vmcnt(6)
	s_barrier
; #define PG8_STAGE(bufoff, gbase, voff) do { _Pragma("unroll") for (int _i = 0; _i < 2; ++_i) \
;         __builtin_amdgcn_global_load_lds((const unsigned*)((const char*)(gbase) + (voff)[_i]), (LAS unsigned*)(lds + (bufoff) + ldsw + _i * 8192), 16, 0, 0); } while (0)
; #define PG8_LDA(dst, b, h) do { _Pragma("unroll") for (int m = 0; m < 4; ++m) _Pragma("unroll") for (int k = 0; k < 2; ++k) dst[m][k] = *(const LAS bf16x8*)(lds + PG8_SA(b, h) + aoff + m * 2048 + k * 1024); } while (0)
; #define PG8_LDB(dst, b, h) do { _Pragma("unroll") for (int n = 0; n < 2; ++n) _Pragma("unroll") for (int k = 0; k < 2; ++k) dst[n][k] = *(const LAS bf16x8*)(lds + PG8_SB(b, h) + boff + n * 2048 + k * 1024); } while (0)
; #define PG8_MMA(ai, bj, At, Bt) do { __builtin_amdgcn_s_setprio(1); _Pragma("unroll") for (int m = 0; m < 4; ++m) _Pragma("unroll") for (int n = 0; n < 2; ++n) _Pragma("unroll") for (int k = 0; k < 2; ++k) \
;         acc[ai][bj][m][n] = __builtin_amdgcn_mfma_f32_16x16x32_bf16(Bt[n][k], At[m][k], acc[ai][bj][m][n], 0, 0, 0); __builtin_amdgcn_s_setprio(0); } while (0)
; #define PG8_WAIT_V(n) asm volatile("s_waitcnt vmcnt(" #n ")" ::: "memory")
; #define PG8_WAIT_L(n) asm volatile("s_waitcnt lgkmcnt(" #n ")" ::: "memory")
; #define PG8_BAR __builtin_amdgcn_s_barrier()
; #define PG8_SCHED __builtin_amdgcn_sched_barrier(0)
; template <class Epi, class Sched>
; __device__ __forceinline__ void gemm_phase(LAS unsigned char* lds, const Gemm g, const Sched& S, const Epi& E) {
;     ...
;             PG8_BAR; PG8_WAIT_L(0); PG8_MMA(1, 0, At, B0); PG8_BAR; PG8_SCHED;
;             PG8_STAGE(PG8_SB(0, 1), b2 + hstepB, voffB);
;             PG8_WAIT_V(6); PG8_BAR; PG8_MMA(1, 1, At, B1); PG8_BAR;
;             PG8_LDB(B0, 1, 0); PG8_SCHED; PG8_LDA(At, 1, 0); PG8_STAGE(PG8_SA(0, 1), a2 + hstepA, voffA);
;             PG8_WAIT_L(8); PG8_BAR; PG8_WAIT_L(0); PG8_MMA(0, 0, At, B0); PG8_BAR; PG8_SCHED;
;             PG8_LDB(B1, 1, 1); PG8_STAGE(PG8_SB(1, 0), b3, voffB);
;             PG8_BAR; PG8_WAIT_L(0); PG8_MMA(0, 1, At, B1); PG8_BAR;
;             PG8_LDA(At, 1, 1); PG8_STAGE(PG8_SA(1, 0), a3, voffA);
;             PG8_BAR; PG8_WAIT_L(0); PG8_MMA(1, 0, At, B0); PG8_BAR; PG8_SCHED;
	s_setprio 1
	v_mfma_f32_16x16x32_bf16 v[64:67], v[132:135], v[148:151], v[64:67]
	v_mfma_f32_16x16x32_bf16 v[60:63], v[140:143], v[148:151], v[60:63]
	v_mfma_f32_16x16x32_bf16 v[52:55], v[132:135], v[156:159], v[52:55]
	v_mfma_f32_16x16x32_bf16 v[44:47], v[140:143], v[156:159], v[44:47]
	v_mfma_f32_16x16x32_bf16 v[36:39], v[132:135], v[164:167], v[36:39]
	v_mfma_f32_16x16x32_bf16 v[28:31], v[140:143], v[164:167], v[28:31]
	v_mfma_f32_16x16x32_bf16 v[20:23], v[132:135], v[172:175], v[20:23]
	v_mfma_f32_16x16x32_bf16 v[12:15], v[140:143], v[172:175], v[12:15]
	v_mfma_f32_16x16x32_bf16 v[64:67], v[136:139], v[152:155], v[64:67]
	v_mfma_f32_16x16x32_bf16 v[60:63], v[144:147], v[152:155], v[60:63]
	v_mfma_f32_16x16x32_bf16 v[52:55], v[136:139], v[160:163], v[52:55]
	v_mfma_f32_16x16x32_bf16 v[44:47], v[144:147], v[160:163], v[44:47]
	v_mfma_f32_16x16x32_bf16 v[36:39], v[136:139], v[168:171], v[36:39]
	v_mfma_f32_16x16x32_bf16 v[28:31], v[144:147], v[168:171], v[28:31]
	v_mfma_f32_16x16x32_bf16 v[20:23], v[136:139], v[176:179], v[20:23]
	v_mfma_f32_16x16x32_bf16 v[12:15], v[144:147], v[176:179], v[12:15]
	v_mfma_f32_16x16x32_bf16 v[56:59], v[180:183], v[148:151], v[56:59]
	v_mfma_f32_16x16x32_bf16 v[48:51], v[188:191], v[148:151], v[48:51]
	v_mfma_f32_16x16x32_bf16 v[40:43], v[180:183], v[156:159], v[40:43]
	v_mfma_f32_16x16x32_bf16 v[32:35], v[188:191], v[156:159], v[32:35]
	v_mfma_f32_16x16x32_bf16 v[24:27], v[180:183], v[164:167], v[24:27]
	v_mfma_f32_16x16x32_bf16 v[16:19], v[188:191], v[164:167], v[16:19]
	v_mfma_f32_16x16x32_bf16 v[8:11], v[180:183], v[172:175], v[8:11]
	v_mfma_f32_16x16x32_bf16 v[4:7], v[188:191], v[172:175], v[4:7]
	v_mfma_f32_16x16x32_bf16 v[56:59], v[184:187], v[152:155], v[56:59]
	v_mfma_f32_16x16x32_bf16 v[48:51], v[202:205], v[152:155], v[48:51]
	v_mfma_f32_16x16x32_bf16 v[40:43], v[184:187], v[160:163], v[40:43]
	v_mfma_f32_16x16x32_bf16 v[32:35], v[202:205], v[160:163], v[32:35]
	v_mfma_f32_16x16x32_bf16 v[24:27], v[184:187], v[168:171], v[24:27]
	v_mfma_f32_16x16x32_bf16 v[16:19], v[202:205], v[168:171], v[16:19]
	v_mfma_f32_16x16x32_bf16 v[8:11], v[184:187], v[176:179], v[8:11]
	v_mfma_f32_16x16x32_bf16 v[4:7], v[202:205], v[176:179], v[4:7]
	s_setprio 0
	s_add_i32 s52, 0, 0x18000
	v_add_u32_e32 v144, s52, v1
	s_barrier
	ds_read_b128 v[132:135], v144
	ds_read_b128 v[136:139], v144 offset:1024
	ds_read_b128 v[140:143], v144 offset:2048
	ds_read_b128 v[144:147], v144 offset:3072
	s_add_u32 s24, s24, 0x80000
	s_addc_u32 s25, s25, 0
	s_mov_b32 m0, s36
	ds_read_b128 v[148:151], v224 offset:32768
	ds_read_b128 v[152:155], v224 offset:33792
	ds_read_b128 v[156:159], v224 offset:34816
	ds_read_b128 v[160:163], v224 offset:35840
	ds_read_b128 v[164:167], v224 offset:36864
	ds_read_b128 v[168:171], v224 offset:37888
	ds_read_b128 v[172:175], v224 offset:38912
	ds_read_b128 v[176:179], v224 offset:39936
	global_load_lds_dwordx4 v196, s[24:25]
	s_mov_b32 m0, s37
	s_nop 0
	global_load_lds_dwordx4 v194, s[24:25]
	s_add_i32 s24, 0, 0x1c000
	v_add_u32_e32 v202, s24, v1
	ds_read_b128 v[180:183], v202
	ds_read_b128 v[184:187], v202 offset:1024
	ds_read_b128 v[188:191], v202 offset:2048
	ds_read_b128 v[202:205], v202 offset:3072
	s_waitcnt lgkmcnt(0)
	s_barrier
	s_setprio 1
	v_mfma_f32_16x16x32_bf16 v[128:131], v[132:135], v[148:151], v[128:131]
	v_mfma_f32_16x16x32_bf16 v[124:127], v[140:143], v[148:151], v[124:127]
	v_mfma_f32_16x16x32_bf16 v[112:115], v[132:135], v[156:159], v[112:115]
	v_mfma_f32_16x16x32_bf16 v[108:111], v[140:143], v[156:159], v[108:111]
	v_mfma_f32_16x16x32_bf16 v[100:103], v[132:135], v[164:167], v[100:103]
	v_mfma_f32_16x16x32_bf16 v[92:95], v[140:143], v[164:167], v[92:95]
	v_mfma_f32_16x16x32_bf16 v[84:87], v[132:135], v[172:175], v[84:87]
	v_mfma_f32_16x16x32_bf16 v[76:79], v[140:143], v[172:175], v[76:79]
	v_mfma_f32_16x16x32_bf16 v[128:131], v[136:139], v[152:155], v[128:131]
	v_mfma_f32_16x16x32_bf16 v[124:127], v[144:147], v[152:155], v[124:127]
	v_mfma_f32_16x16x32_bf16 v[112:115], v[136:139], v[160:163], v[112:115]
	v_mfma_f32_16x16x32_bf16 v[108:111], v[144:147], v[160:163], v[108:111]
	v_mfma_f32_16x16x32_bf16 v[100:103], v[136:139], v[168:171], v[100:103]
	v_mfma_f32_16x16x32_bf16 v[92:95], v[144:147], v[168:171], v[92:95]
	v_mfma_f32_16x16x32_bf16 v[84:87], v[136:139], v[176:179], v[84:87]
	v_mfma_f32_16x16x32_bf16 v[76:79], v[144:147], v[176:179], v[76:79]
	v_mfma_f32_16x16x32_bf16 v[120:123], v[180:183], v[148:151], v[120:123]
	v_mfma_f32_16x16x32_bf16 v[116:119], v[188:191], v[148:151], v[116:119]
	v_mfma_f32_16x16x32_bf16 v[104:107], v[180:183], v[156:159], v[104:107]
	v_mfma_f32_16x16x32_bf16 v[96:99], v[188:191], v[156:159], v[96:99]
	v_mfma_f32_16x16x32_bf16 v[88:91], v[180:183], v[164:167], v[88:91]
	v_mfma_f32_16x16x32_bf16 v[80:83], v[188:191], v[164:167], v[80:83]
	v_mfma_f32_16x16x32_bf16 v[72:75], v[180:183], v[172:175], v[72:75]
	v_mfma_f32_16x16x32_bf16 v[68:71], v[188:191], v[172:175], v[68:71]
	v_mfma_f32_16x16x32_bf16 v[120:123], v[184:187], v[152:155], v[120:123]
	v_mfma_f32_16x16x32_bf16 v[116:119], v[202:205], v[152:155], v[116:119]
	v_mfma_f32_16x16x32_bf16 v[104:107], v[184:187], v[160:163], v[104:107]
	v_mfma_f32_16x16x32_bf16 v[96:99], v[202:205], v[160:163], v[96:99]
	v_mfma_f32_16x16x32_bf16 v[88:91], v[184:187], v[168:171], v[88:91]
	v_mfma_f32_16x16x32_bf16 v[80:83], v[202:205], v[168:171], v[80:83]
	v_mfma_f32_16x16x32_bf16 v[72:75], v[184:187], v[176:179], v[72:75]
	v_mfma_f32_16x16x32_bf16 v[68:71], v[202:205], v[176:179], v[68:71]
	s_setprio 0
	s_barrier
; __device__ __forceinline__ int opaque_tid() { int t = threadIdx.x; asm volatile("" : "+v"(t)); return t; }
; #define PG8_STAGE(bufoff, gbase, voff) do { _Pragma("unroll") for (int _i = 0; _i < 2; ++_i) \
;         __builtin_amdgcn_global_load_lds((const unsigned*)((const char*)(gbase) + (voff)[_i]), (LAS unsigned*)(lds + (bufoff) + ldsw + _i * 8192), 16, 0, 0); } while (0)
; #define PG8_LDA(dst, b, h) do { _Pragma("unroll") for (int m = 0; m < 4; ++m) _Pragma("unroll") for (int k = 0; k < 2; ++k) dst[m][k] = *(const LAS bf16x8*)(lds + PG8_SA(b, h) + aoff + m * 2048 + k * 1024); } while (0)
; #define PG8_MMA(ai, bj, At, Bt) do { __builtin_amdgcn_s_setprio(1); _Pragma("unroll") for (int m = 0; m < 4; ++m) _Pragma("unroll") for (int n = 0; n < 2; ++n) _Pragma("unroll") for (int k = 0; k < 2; ++k) \
;         acc[ai][bj][m][n] = __builtin_amdgcn_mfma_f32_16x16x32_bf16(Bt[n][k], At[m][k], acc[ai][bj][m][n], 0, 0, 0); __builtin_amdgcn_s_setprio(0); } while (0)
; #define PG8_WAIT_V(n) asm volatile("s_waitcnt vmcnt(" #n ")" ::: "memory")
; #define PG8_WAIT_L(n) asm volatile("s_waitcnt lgkmcnt(" #n ")" ::: "memory")
; #define PG8_BAR __builtin_amdgcn_s_barrier()
; #define PG8_SCHED __builtin_amdgcn_sched_barrier(0)
;     __device__ __forceinline__ void operator()(const f32x4 (&acc)[2][2][4][2], const Unit& u, int wr, int wc, int, int) const {
;         const int ol_ = opaque_tid() & 63, fr = ol_ & 15, fq = ol_ >> 4;
;         const int row0 = u.pm * BM + wr * 64 + fr, col0 = u.pn * BM + wc * 32 + 8 * fq;
;         u32x4 cin[2][4][2];
; #pragma unroll
;         for (int ai = 0; ai < 2; ++ai)
; #pragma unroll
;             for (int m = 0; m < 4; ++m)
; #pragma unroll
;                 for (int bj = 0; bj < 2; ++bj) cin[ai][m][bj] = *(const u32x4*)(C + (size_t)(row0 + ai * HALF + m * 16) * ldc + col0 + bj * HALF);
; template <class Epi, class Sched>
; __device__ __forceinline__ void gemm_phase(LAS unsigned char* lds, const Gemm g, const Sched& S, const Epi& E) {
;     ...
;             PG8_LDA(At, 1, 1); PG8_STAGE(PG8_SA(1, 0), a3, voffA);
;             PG8_BAR; PG8_WAIT_L(0); PG8_MMA(1, 0, At, B0); PG8_BAR; PG8_SCHED;
;             PG8_STAGE(PG8_SB(1, 1), b3 + hstepB, voffB);
;             PG8_WAIT_V(6); PG8_BAR; PG8_MMA(1, 1, At, B1); PG8_BAR;
	ds_read_b128 v[148:151], v224 offset:49152
	ds_read_b128 v[152:155], v224 offset:50176
	ds_read_b128 v[156:159], v224 offset:51200
	ds_read_b128 v[160:163], v224 offset:52224
	ds_read_b128 v[164:167], v224 offset:53248
	ds_read_b128 v[168:171], v224 offset:54272
	ds_read_b128 v[172:175], v224 offset:55296
	ds_read_b128 v[176:179], v224 offset:56320
	s_add_i32 s25, s52, s30
	v_lshl_add_u64 v[206:207], v[206:207], 0, s[8:9]
	s_mov_b32 m0, s25
	s_nop 0
	global_load_lds_dwordx4 v[206:207], off
	v_lshl_add_u64 v[206:207], v[208:209], 0, s[8:9]
	s_add_i32 m0, s25, 0x2000
	s_nop 0
	global_load_lds_dwordx4 v[206:207], off
	s_mov_b32 m0, s40
	v_lshl_add_u64 v[206:207], v[210:211], 0, s[8:9]
	s_nop 0
	global_load_lds_dwordx4 v[206:207], off
	v_lshl_add_u64 v[206:207], v[212:213], 0, s[8:9]
	s_mov_b32 m0, s41
	s_nop 0
	global_load_lds_dwordx4 v[206:207], off
	s_add_u32 s20, s20, 0x80080
	s_addc_u32 s21, s21, 0
	s_add_i32 s24, s24, s30
	s_mov_b32 m0, s24
	s_nop 0
	global_load_lds_dwordx4 v2, s[20:21]
	s_add_i32 m0, s24, 0x2000
	s_nop 0
	global_load_lds_dwordx4 v192, s[20:21]
	s_waitcnt lgkmcnt(0)
	s_waitcnt vmcnt(6)
	s_barrier
	s_setprio 1
	v_mfma_f32_16x16x32_bf16 v[64:67], v[132:135], v[148:151], v[64:67]
	v_mfma_f32_16x16x32_bf16 v[60:63], v[140:143], v[148:151], v[60:63]
	v_mfma_f32_16x16x32_bf16 v[52:55], v[132:135], v[156:159], v[52:55]
	v_mfma_f32_16x16x32_bf16 v[44:47], v[140:143], v[156:159], v[44:47]
	v_mfma_f32_16x16x32_bf16 v[36:39], v[132:135], v[164:167], v[36:39]
	v_mfma_f32_16x16x32_bf16 v[28:31], v[140:143], v[164:167], v[28:31]
	v_mfma_f32_16x16x32_bf16 v[20:23], v[132:135], v[172:175], v[20:23]
	v_mfma_f32_16x16x32_bf16 v[12:15], v[140:143], v[172:175], v[12:15]
	v_mfma_f32_16x16x32_bf16 v[64:67], v[136:139], v[152:155], v[64:67]
	v_mfma_f32_16x16x32_bf16 v[60:63], v[144:147], v[152:155], v[60:63]
	v_mfma_f32_16x16x32_bf16 v[52:55], v[136:139], v[160:163], v[52:55]
	v_mfma_f32_16x16x32_bf16 v[44:47], v[144:147], v[160:163], v[44:47]
	v_mfma_f32_16x16x32_bf16 v[36:39], v[136:139], v[168:171], v[36:39]
	v_mfma_f32_16x16x32_bf16 v[28:31], v[144:147], v[168:171], v[28:31]
	v_mfma_f32_16x16x32_bf16 v[20:23], v[136:139], v[176:179], v[20:23]
	v_mfma_f32_16x16x32_bf16 v[12:15], v[144:147], v[176:179], v[12:15]
	v_mfma_f32_16x16x32_bf16 v[56:59], v[180:183], v[148:151], v[56:59]
	v_mfma_f32_16x16x32_bf16 v[48:51], v[188:191], v[148:151], v[48:51]
	v_mfma_f32_16x16x32_bf16 v[40:43], v[180:183], v[156:159], v[40:43]
	v_mfma_f32_16x16x32_bf16 v[32:35], v[188:191], v[156:159], v[32:35]
	v_mfma_f32_16x16x32_bf16 v[24:27], v[180:183], v[164:167], v[24:27]
	v_mfma_f32_16x16x32_bf16 v[16:19], v[188:191], v[164:167], v[16:19]
	v_mfma_f32_16x16x32_bf16 v[8:11], v[180:183], v[172:175], v[8:11]
	v_mfma_f32_16x16x32_bf16 v[4:7], v[188:191], v[172:175], v[4:7]
	v_mfma_f32_16x16x32_bf16 v[56:59], v[184:187], v[152:155], v[56:59]
	v_mfma_f32_16x16x32_bf16 v[48:51], v[202:205], v[152:155], v[48:51]
	v_mfma_f32_16x16x32_bf16 v[40:43], v[184:187], v[160:163], v[40:43]
	v_mfma_f32_16x16x32_bf16 v[32:35], v[202:205], v[160:163], v[32:35]
	v_mfma_f32_16x16x32_bf16 v[24:27], v[184:187], v[168:171], v[24:27]
	v_mfma_f32_16x16x32_bf16 v[16:19], v[202:205], v[168:171], v[16:19]
	v_mfma_f32_16x16x32_bf16 v[8:11], v[184:187], v[176:179], v[8:11]
	v_mfma_f32_16x16x32_bf16 v[4:7], v[202:205], v[176:179], v[4:7]
	s_setprio 0
	s_add_i32 s51, s51, 2
	s_add_u32 s6, s6, 0x100
	s_addc_u32 s7, s7, 0
	s_add_u32 s49, s49, 0x100
	s_addc_u32 s50, s50, 0
	s_cmp_gt_u32 s51, 29
	s_barrier
	s_cbranch_scc0 .LBB0_966
	v_mov_b32_e32 v133, v0
	s_lshl_b32 s1, s46, 8
	s_add_i32 s1, s1, s38
	v_and_or_b32 v132, v133, 15, s1
	s_lshl_b32 s1, s45, 8
	v_lshrrev_b32_e32 v133, 1, v133
	v_and_or_b32 v133, v133, 24, s1
	v_or_b32_e32 v134, s39, v133
	v_ashrrev_i32_e32 v135, 31, v134
	v_lshlrev_b64 v[202:203], 1, v[134:135]
	v_ashrrev_i32_e32 v133, 31, v132
	v_lshl_add_u64 v[134:135], s[88:89], 0, v[202:203]
	v_lshlrev_b64 v[226:227], 12, v[132:133]
	v_lshl_add_u64 v[136:137], v[134:135], 0, v[226:227]
	global_load_dwordx4 v[216:219], v[136:137], off
	global_load_dwordx4 v[188:191], v[136:137], off offset:256
	v_or_b32_e32 v136, 16, v132
	v_ashrrev_i32_e32 v137, 31, v136
	v_lshlrev_b64 v[222:223], 12, v[136:137]
	v_lshl_add_u64 v[136:137], v[134:135], 0, v[222:223]
	global_load_dwordx4 v[184:187], v[136:137], off
	global_load_dwordx4 v[180:183], v[136:137], off offset:256
	v_or_b32_e32 v136, 32, v132
	v_ashrrev_i32_e32 v137, 31, v136
	v_lshlrev_b64 v[220:221], 12, v[136:137]
	v_lshl_add_u64 v[136:137], v[134:135], 0, v[220:221]
	global_load_dwordx4 v[176:179], v[136:137], off
	global_load_dwordx4 v[168:171], v[136:137], off offset:256
	v_or_b32_e32 v132, 48, v132
	v_ashrrev_i32_e32 v133, 31, v132
	v_lshlrev_b64 v[212:213], 12, v[132:133]
	v_lshl_add_u64 v[132:133], v[134:135], 0, v[212:213]
	global_load_dwordx4 v[172:175], v[132:133], off
	global_load_dwordx4 v[164:167], v[132:133], off offset:256
	s_mov_b64 s[6:7], 0x80000
	v_lshl_add_u64 v[210:211], v[226:227], 0, s[6:7]
	v_lshl_add_u64 v[132:133], v[134:135], 0, v[210:211]
	global_load_dwordx4 v[160:163], v[132:133], off
	global_load_dwordx4 v[156:159], v[132:133], off offset:256
	s_mov_b64 s[6:7], 0x90000
	v_lshl_add_u64 v[208:209], v[226:227], 0, s[6:7]
	v_lshl_add_u64 v[132:133], v[134:135], 0, v[208:209]
	global_load_dwordx4 v[152:155], v[132:133], off
	global_load_dwordx4 v[148:151], v[132:133], off offset:256
	s_mov_b64 s[6:7], 0xa0000
	v_lshl_add_u64 v[206:207], v[226:227], 0, s[6:7]
	v_lshl_add_u64 v[132:133], v[134:135], 0, v[206:207]
	global_load_dwordx4 v[144:147], v[132:133], off
	global_load_dwordx4 v[140:143], v[132:133], off offset:256
	s_mov_b64 s[6:7], 0xb0000
	v_lshl_add_u64 v[204:205], v[226:227], 0, s[6:7]
	v_lshl_add_u64 v[132:133], v[134:135], 0, v[204:205]
	global_load_dwordx4 v[136:139], v[132:133], off
	s_nop 0
	global_load_dwordx4 v[132:135], v[132:133], off offset:256
	s_and_b64 vcc, exec, s[42:43]
	s_mov_b32 s45, s0
	s_mov_b32 s46, s14
	s_mov_b64 s[20:21], s[18:19]
	s_mov_b64 s[6:7], s[4:5]
	s_waitcnt vmcnt(0)
; __device__ __forceinline__ unsigned cvt_pk_bf16(float lo, float hi) { const f32x2 v = {lo, hi}; const bf16v2_ r = __builtin_convertvector(v, bf16v2_); return __builtin_bit_cast(unsigned, r); }
; __device__ __forceinline__ float bflo(unsigned w) { return __uint_as_float(w << 16); }
; __device__ __forceinline__ float bfhi(unsigned w) { return __uint_as_float(w & 0xffff0000u); }
;     __device__ __forceinline__ void operator()(const f32x4 (&acc)[2][2][4][2], const Unit& u, int wr, int wc, int, int) const {
;     ...
; #pragma unroll
;         for (int ai = 0; ai < 2; ++ai)
; #pragma unroll
;             for (int m = 0; m < 4; ++m)
; #pragma unroll
;                 for (int bj = 0; bj < 2; ++bj) { const u32x4 c = cin[ai][m][bj]; const f32x4 v0 = acc[ai][bj][m][0], v1 = acc[ai][bj][m][1];
;                     u32x4 w; w.x = cvt_pk_bf16(bflo(c.x) + v0[0], bfhi(c.x) + v0[1]); w.y = cvt_pk_bf16(bflo(c.y) + v0[2], bfhi(c.y) + v0[3]);
;                     w.z = cvt_pk_bf16(bflo(c.z) + v1[0], bfhi(c.z) + v1[1]); w.w = cvt_pk_bf16(bflo(c.w) + v1[2], bfhi(c.w) + v1[3]);
;                     *(u32x4*)(C + (size_t)(row0 + ai * HALF + m * 16) * ldc + col0 + bj * HALF) = w; }
	v_lshlrev_b32_e32 v228, 16, v216
	v_and_b32_e32 v229, 0xffff0000, v216
	v_lshlrev_b32_e32 v216, 16, v217
	v_and_b32_e32 v217, 0xffff0000, v217
	v_pk_add_f32 v[128:129], v[128:129], v[228:229]
	v_pk_add_f32 v[130:131], v[130:131], v[216:217]
	v_cvt_pk_bf16_f32 v128, v128, v129
	v_cvt_pk_bf16_f32 v129, v130, v131
	v_lshlrev_b32_e32 v130, 16, v218
	v_and_b32_e32 v131, 0xffff0000, v218
	v_pk_add_f32 v[124:125], v[124:125], v[130:131]
	s_nop 0
	v_cvt_pk_bf16_f32 v130, v124, v125
	v_lshlrev_b32_e32 v124, 16, v219
	v_and_b32_e32 v125, 0xffff0000, v219
	v_pk_add_f32 v[124:125], v[126:127], v[124:125]
	v_lshlrev_b32_e32 v126, 16, v188
	v_and_b32_e32 v127, 0xffff0000, v188
	v_pk_add_f32 v[120:121], v[120:121], v[126:127]
	v_lshlrev_b32_e32 v126, 16, v189
	v_and_b32_e32 v127, 0xffff0000, v189
	v_pk_add_f32 v[122:123], v[122:123], v[126:127]
	v_cvt_pk_bf16_f32 v120, v120, v121
	v_cvt_pk_bf16_f32 v121, v122, v123
	v_lshlrev_b32_e32 v122, 16, v190
	v_and_b32_e32 v123, 0xffff0000, v190
	v_pk_add_f32 v[116:117], v[116:117], v[122:123]
	v_cvt_pk_bf16_f32 v131, v124, v125
	v_cvt_pk_bf16_f32 v122, v116, v117
	v_lshlrev_b32_e32 v116, 16, v191
	v_and_b32_e32 v117, 0xffff0000, v191
	v_pk_add_f32 v[116:117], v[118:119], v[116:117]
	v_lshl_add_u64 v[124:125], s[88:89], 0, v[226:227]
	v_cvt_pk_bf16_f32 v123, v116, v117
	v_lshlrev_b32_e32 v116, 16, v184
	v_and_b32_e32 v117, 0xffff0000, v184
	v_pk_add_f32 v[112:113], v[112:113], v[116:117]
	v_lshlrev_b32_e32 v116, 16, v185
	v_and_b32_e32 v117, 0xffff0000, v185
	v_pk_add_f32 v[114:115], v[114:115], v[116:117]
	v_cvt_pk_bf16_f32 v112, v112, v113
	v_cvt_pk_bf16_f32 v113, v114, v115
	v_lshlrev_b32_e32 v114, 16, v186
	v_and_b32_e32 v115, 0xffff0000, v186
	v_pk_add_f32 v[108:109], v[108:109], v[114:115]
	v_lshl_add_u64 v[124:125], v[124:125], 0, v[202:203]
	v_cvt_pk_bf16_f32 v114, v108, v109
	v_lshlrev_b32_e32 v108, 16, v187
	v_and_b32_e32 v109, 0xffff0000, v187
	v_pk_add_f32 v[108:109], v[110:111], v[108:109]
	v_lshlrev_b32_e32 v110, 16, v180
	v_and_b32_e32 v111, 0xffff0000, v180
	v_pk_add_f32 v[104:105], v[104:105], v[110:111]
	v_lshlrev_b32_e32 v110, 16, v181
	v_and_b32_e32 v111, 0xffff0000, v181
	v_pk_add_f32 v[106:107], v[106:107], v[110:111]
	v_cvt_pk_bf16_f32 v104, v104, v105
	v_cvt_pk_bf16_f32 v105, v106, v107
	v_lshlrev_b32_e32 v106, 16, v182
	v_and_b32_e32 v107, 0xffff0000, v182
	v_pk_add_f32 v[96:97], v[96:97], v[106:107]
	v_cvt_pk_bf16_f32 v115, v108, v109
	v_cvt_pk_bf16_f32 v106, v96, v97
	v_lshlrev_b32_e32 v96, 16, v183
	v_and_b32_e32 v97, 0xffff0000, v183
	v_pk_add_f32 v[96:97], v[98:99], v[96:97]
	v_lshlrev_b32_e32 v98, 16, v177
	v_cvt_pk_bf16_f32 v107, v96, v97
	v_lshlrev_b32_e32 v96, 16, v176
	v_and_b32_e32 v97, 0xffff0000, v176
	v_and_b32_e32 v99, 0xffff0000, v177
	v_pk_add_f32 v[96:97], v[100:101], v[96:97]
	v_pk_add_f32 v[98:99], v[102:103], v[98:99]
	v_cvt_pk_bf16_f32 v96, v96, v97
	v_cvt_pk_bf16_f32 v97, v98, v99
	v_lshlrev_b32_e32 v98, 16, v178
	v_and_b32_e32 v99, 0xffff0000, v178
	v_pk_add_f32 v[92:93], v[92:93], v[98:99]
	v_lshl_add_u64 v[108:109], s[88:89], 0, v[222:223]
	v_cvt_pk_bf16_f32 v98, v92, v93
	v_lshlrev_b32_e32 v92, 16, v179
	v_and_b32_e32 v93, 0xffff0000, v179
	v_pk_add_f32 v[92:93], v[94:95], v[92:93]
	v_lshlrev_b32_e32 v94, 16, v168
	v_and_b32_e32 v95, 0xffff0000, v168
	v_pk_add_f32 v[88:89], v[88:89], v[94:95]
	v_lshlrev_b32_e32 v94, 16, v169
	v_and_b32_e32 v95, 0xffff0000, v169
	v_pk_add_f32 v[90:91], v[90:91], v[94:95]
	v_cvt_pk_bf16_f32 v88, v88, v89
	v_cvt_pk_bf16_f32 v89, v90, v91
	v_lshlrev_b32_e32 v90, 16, v170
	v_and_b32_e32 v91, 0xffff0000, v170
	v_pk_add_f32 v[80:81], v[80:81], v[90:91]
	v_cvt_pk_bf16_f32 v99, v92, v93
	v_cvt_pk_bf16_f32 v90, v80, v81
	v_lshlrev_b32_e32 v80, 16, v171
	v_and_b32_e32 v81, 0xffff0000, v171
	v_pk_add_f32 v[80:81], v[82:83], v[80:81]
	v_lshlrev_b32_e32 v82, 16, v173
	v_cvt_pk_bf16_f32 v91, v80, v81
	v_lshlrev_b32_e32 v80, 16, v172
	v_and_b32_e32 v81, 0xffff0000, v172
	v_and_b32_e32 v83, 0xffff0000, v173
	v_pk_add_f32 v[80:81], v[84:85], v[80:81]
	v_pk_add_f32 v[82:83], v[86:87], v[82:83]
	v_cvt_pk_bf16_f32 v80, v80, v81
	v_cvt_pk_bf16_f32 v81, v82, v83
	v_lshlrev_b32_e32 v82, 16, v174
	v_and_b32_e32 v83, 0xffff0000, v174
	v_pk_add_f32 v[76:77], v[76:77], v[82:83]
	v_lshl_add_u64 v[92:93], s[88:89], 0, v[220:221]
	v_cvt_pk_bf16_f32 v82, v76, v77
	v_lshlrev_b32_e32 v76, 16, v175
	v_and_b32_e32 v77, 0xffff0000, v175
	v_pk_add_f32 v[76:77], v[78:79], v[76:77]
	v_lshlrev_b32_e32 v78, 16, v164
	v_and_b32_e32 v79, 0xffff0000, v164
	v_pk_add_f32 v[72:73], v[72:73], v[78:79]
	v_lshlrev_b32_e32 v78, 16, v165
	v_and_b32_e32 v79, 0xffff0000, v165
	v_pk_add_f32 v[74:75], v[74:75], v[78:79]
	v_cvt_pk_bf16_f32 v72, v72, v73
	v_cvt_pk_bf16_f32 v73, v74, v75
	v_lshlrev_b32_e32 v74, 16, v166
	v_and_b32_e32 v75, 0xffff0000, v166
	v_pk_add_f32 v[68:69], v[68:69], v[74:75]
	v_cvt_pk_bf16_f32 v83, v76, v77
	v_cvt_pk_bf16_f32 v74, v68, v69
	v_lshlrev_b32_e32 v68, 16, v167
	v_and_b32_e32 v69, 0xffff0000, v167
	v_pk_add_f32 v[68:69], v[70:71], v[68:69]
	v_lshl_add_u64 v[76:77], s[88:89], 0, v[212:213]
	v_cvt_pk_bf16_f32 v75, v68, v69
	v_lshlrev_b32_e32 v68, 16, v160
	v_and_b32_e32 v69, 0xffff0000, v160
	v_pk_add_f32 v[64:65], v[64:65], v[68:69]
	v_lshlrev_b32_e32 v68, 16, v161
	v_and_b32_e32 v69, 0xffff0000, v161
	v_pk_add_f32 v[66:67], v[66:67], v[68:69]
	v_cvt_pk_bf16_f32 v64, v64, v65
	v_cvt_pk_bf16_f32 v65, v66, v67
	v_lshlrev_b32_e32 v66, 16, v162
	v_and_b32_e32 v67, 0xffff0000, v162
	v_pk_add_f32 v[60:61], v[60:61], v[66:67]
	v_lshl_add_u64 v[108:109], v[108:109], 0, v[202:203]
	v_cvt_pk_bf16_f32 v66, v60, v61
	v_lshlrev_b32_e32 v60, 16, v163
; __device__ __forceinline__ unsigned cvt_pk_bf16(float lo, float hi) { const f32x2 v = {lo, hi}; const bf16v2_ r = __builtin_convertvector(v, bf16v2_); return __builtin_bit_cast(unsigned, r); }
; __device__ __forceinline__ float bflo(unsigned w) { return __uint_as_float(w << 16); }
; __device__ __forceinline__ float bfhi(unsigned w) { return __uint_as_float(w & 0xffff0000u); }
;     __device__ __forceinline__ void operator()(const f32x4 (&acc)[2][2][4][2], const Unit& u, int wr, int wc, int, int) const {
;     ...
; #pragma unroll
;         for (int ai = 0; ai < 2; ++ai)
; #pragma unroll
;             for (int m = 0; m < 4; ++m)
; #pragma unroll
;                 for (int bj = 0; bj < 2; ++bj) { const u32x4 c = cin[ai][m][bj]; const f32x4 v0 = acc[ai][bj][m][0], v1 = acc[ai][bj][m][1];
;                     u32x4 w; w.x = cvt_pk_bf16(bflo(c.x) + v0[0], bfhi(c.x) + v0[1]); w.y = cvt_pk_bf16(bflo(c.y) + v0[2], bfhi(c.y) + v0[3]);
;                     w.z = cvt_pk_bf16(bflo(c.z) + v1[0], bfhi(c.z) + v1[1]); w.w = cvt_pk_bf16(bflo(c.w) + v1[2], bfhi(c.w) + v1[3]);
;                     *(u32x4*)(C + (size_t)(row0 + ai * HALF + m * 16) * ldc + col0 + bj * HALF) = w; }
	v_and_b32_e32 v61, 0xffff0000, v163
	v_pk_add_f32 v[60:61], v[62:63], v[60:61]
	v_lshlrev_b32_e32 v62, 16, v156
	v_and_b32_e32 v63, 0xffff0000, v156
	v_pk_add_f32 v[56:57], v[56:57], v[62:63]
	v_lshlrev_b32_e32 v62, 16, v157
	v_and_b32_e32 v63, 0xffff0000, v157
	v_pk_add_f32 v[58:59], v[58:59], v[62:63]
	v_cvt_pk_bf16_f32 v56, v56, v57
	v_cvt_pk_bf16_f32 v57, v58, v59
	v_lshlrev_b32_e32 v58, 16, v158
	v_and_b32_e32 v59, 0xffff0000, v158
	v_pk_add_f32 v[48:49], v[48:49], v[58:59]
	v_cvt_pk_bf16_f32 v67, v60, v61
	v_cvt_pk_bf16_f32 v58, v48, v49
	v_lshlrev_b32_e32 v48, 16, v159
	v_and_b32_e32 v49, 0xffff0000, v159
	v_pk_add_f32 v[48:49], v[50:51], v[48:49]
	v_lshlrev_b32_e32 v50, 16, v153
	v_cvt_pk_bf16_f32 v59, v48, v49
	v_lshlrev_b32_e32 v48, 16, v152
	v_and_b32_e32 v49, 0xffff0000, v152
	v_and_b32_e32 v51, 0xffff0000, v153
	v_pk_add_f32 v[48:49], v[52:53], v[48:49]
	v_pk_add_f32 v[50:51], v[54:55], v[50:51]
	v_cvt_pk_bf16_f32 v48, v48, v49
	v_cvt_pk_bf16_f32 v49, v50, v51
	v_lshlrev_b32_e32 v50, 16, v154
	v_and_b32_e32 v51, 0xffff0000, v154
	v_pk_add_f32 v[44:45], v[44:45], v[50:51]
	v_lshl_add_u64 v[60:61], s[88:89], 0, v[210:211]
	v_cvt_pk_bf16_f32 v50, v44, v45
	v_lshlrev_b32_e32 v44, 16, v155
	v_and_b32_e32 v45, 0xffff0000, v155
	v_pk_add_f32 v[44:45], v[46:47], v[44:45]
	v_lshlrev_b32_e32 v46, 16, v148
	v_and_b32_e32 v47, 0xffff0000, v148
	v_pk_add_f32 v[40:41], v[40:41], v[46:47]
	v_lshlrev_b32_e32 v46, 16, v149
	v_and_b32_e32 v47, 0xffff0000, v149
	v_pk_add_f32 v[42:43], v[42:43], v[46:47]
	v_cvt_pk_bf16_f32 v40, v40, v41
	v_cvt_pk_bf16_f32 v41, v42, v43
	v_lshlrev_b32_e32 v42, 16, v150
	v_and_b32_e32 v43, 0xffff0000, v150
	v_pk_add_f32 v[32:33], v[32:33], v[42:43]
	v_cvt_pk_bf16_f32 v51, v44, v45
	v_cvt_pk_bf16_f32 v42, v32, v33
	v_lshlrev_b32_e32 v32, 16, v151
	v_and_b32_e32 v33, 0xffff0000, v151
	v_pk_add_f32 v[32:33], v[34:35], v[32:33]
	v_lshlrev_b32_e32 v34, 16, v145
	v_cvt_pk_bf16_f32 v43, v32, v33
	v_lshlrev_b32_e32 v32, 16, v144
	v_and_b32_e32 v33, 0xffff0000, v144
	v_and_b32_e32 v35, 0xffff0000, v145
	v_pk_add_f32 v[32:33], v[36:37], v[32:33]
	v_pk_add_f32 v[34:35], v[38:39], v[34:35]
	v_cvt_pk_bf16_f32 v32, v32, v33
	v_cvt_pk_bf16_f32 v33, v34, v35
	v_lshlrev_b32_e32 v34, 16, v146
	v_and_b32_e32 v35, 0xffff0000, v146
	v_pk_add_f32 v[28:29], v[28:29], v[34:35]
	v_lshl_add_u64 v[44:45], s[88:89], 0, v[208:209]
	v_cvt_pk_bf16_f32 v34, v28, v29
	v_lshlrev_b32_e32 v28, 16, v147
	v_and_b32_e32 v29, 0xffff0000, v147
	v_pk_add_f32 v[28:29], v[30:31], v[28:29]
	v_lshlrev_b32_e32 v30, 16, v140
	v_and_b32_e32 v31, 0xffff0000, v140
	v_pk_add_f32 v[24:25], v[24:25], v[30:31]
	v_lshlrev_b32_e32 v30, 16, v141
	v_and_b32_e32 v31, 0xffff0000, v141
	v_pk_add_f32 v[26:27], v[26:27], v[30:31]
	v_cvt_pk_bf16_f32 v24, v24, v25
	v_cvt_pk_bf16_f32 v25, v26, v27
	v_lshlrev_b32_e32 v26, 16, v142
	v_and_b32_e32 v27, 0xffff0000, v142
	v_pk_add_f32 v[16:17], v[16:17], v[26:27]
	v_cvt_pk_bf16_f32 v35, v28, v29
	v_cvt_pk_bf16_f32 v26, v16, v17
	v_lshlrev_b32_e32 v16, 16, v143
	v_and_b32_e32 v17, 0xffff0000, v143
	v_pk_add_f32 v[16:17], v[18:19], v[16:17]
	v_lshlrev_b32_e32 v18, 16, v137
	v_cvt_pk_bf16_f32 v27, v16, v17
	v_lshlrev_b32_e32 v16, 16, v136
	v_and_b32_e32 v17, 0xffff0000, v136
	v_and_b32_e32 v19, 0xffff0000, v137
	v_pk_add_f32 v[16:17], v[20:21], v[16:17]
	v_pk_add_f32 v[18:19], v[22:23], v[18:19]
	v_cvt_pk_bf16_f32 v16, v16, v17
	v_cvt_pk_bf16_f32 v17, v18, v19
	v_lshlrev_b32_e32 v18, 16, v138
	v_and_b32_e32 v19, 0xffff0000, v138
	v_pk_add_f32 v[12:13], v[12:13], v[18:19]
	v_lshl_add_u64 v[28:29], s[88:89], 0, v[206:207]
	v_cvt_pk_bf16_f32 v18, v12, v13
	v_lshlrev_b32_e32 v12, 16, v139
	v_and_b32_e32 v13, 0xffff0000, v139
	v_pk_add_f32 v[12:13], v[14:15], v[12:13]
	v_lshlrev_b32_e32 v14, 16, v132
	v_and_b32_e32 v15, 0xffff0000, v132
	v_pk_add_f32 v[8:9], v[8:9], v[14:15]
	v_lshlrev_b32_e32 v14, 16, v133
	v_and_b32_e32 v15, 0xffff0000, v133
	v_pk_add_f32 v[10:11], v[10:11], v[14:15]
	v_cvt_pk_bf16_f32 v8, v8, v9
	v_cvt_pk_bf16_f32 v9, v10, v11
	v_lshlrev_b32_e32 v10, 16, v134
	v_and_b32_e32 v11, 0xffff0000, v134
	v_pk_add_f32 v[4:5], v[4:5], v[10:11]
	v_cvt_pk_bf16_f32 v19, v12, v13
	v_cvt_pk_bf16_f32 v10, v4, v5
	v_lshlrev_b32_e32 v4, 16, v135
	v_and_b32_e32 v5, 0xffff0000, v135
	v_lshl_add_u64 v[12:13], s[88:89], 0, v[204:205]
	v_pk_add_f32 v[4:5], v[6:7], v[4:5]
	v_lshl_add_u64 v[92:93], v[92:93], 0, v[202:203]
	v_lshl_add_u64 v[76:77], v[76:77], 0, v[202:203]
	v_lshl_add_u64 v[60:61], v[60:61], 0, v[202:203]
	v_lshl_add_u64 v[44:45], v[44:45], 0, v[202:203]
	v_lshl_add_u64 v[28:29], v[28:29], 0, v[202:203]
	v_lshl_add_u64 v[12:13], v[12:13], 0, v[202:203]
	v_cvt_pk_bf16_f32 v11, v4, v5
	global_store_dwordx4 v[124:125], v[128:131], off
	global_store_dwordx4 v[124:125], v[120:123], off offset:256
	global_store_dwordx4 v[108:109], v[112:115], off
	global_store_dwordx4 v[108:109], v[104:107], off offset:256
	global_store_dwordx4 v[92:93], v[96:99], off
	global_store_dwordx4 v[92:93], v[88:91], off offset:256
	global_store_dwordx4 v[76:77], v[80:83], off
	global_store_dwordx4 v[76:77], v[72:75], off offset:256
	global_store_dwordx4 v[60:61], v[64:67], off
	global_store_dwordx4 v[60:61], v[56:59], off offset:256
	global_store_dwordx4 v[44:45], v[48:51], off
	global_store_dwordx4 v[44:45], v[40:43], off offset:256
	global_store_dwordx4 v[28:29], v[32:35], off
	global_store_dwordx4 v[28:29], v[24:27], off offset:256
	global_store_dwordx4 v[12:13], v[16:19], off
	global_store_dwordx4 v[12:13], v[8:11], off offset:256
	s_cbranch_vccz .LBB0_959
	s_waitcnt vmcnt(0)
	s_cmpk_gt_u32 s2, 0xff
	s_cbranch_scc1 .LBB0_970
	s_barrier

; #define PG8_STAGE(bufoff, gbase, voff) do { _Pragma("unroll") for (int _i = 0; _i < 2; ++_i) \
;         __builtin_amdgcn_global_load_lds((const unsigned*)((const char*)(gbase) + (voff)[_i]), (LAS unsigned*)(lds + (bufoff) + ldsw + _i * 8192), 16, 0, 0); } while (0)
; #define PG8_WAIT_V(n) asm volatile("s_waitcnt vmcnt(" #n ")" ::: "memory")
; #define PG8_BAR __builtin_amdgcn_s_barrier()
; template <class Epi, class Sched>
; __device__ __forceinline__ void gemm_phase(LAS unsigned char* lds, const Gemm g, const Sched& S, const Epi& E) {
;     ...
;     const char* cA = (const char*)g.A + (size_t)cur.pm * tstepA; const char* cB = (const char*)g.Bt + (size_t)cur.pn * tstepB;
;     S.a_ready(cur);
;     PG8_STAGE(PG8_SB(0, 0), cB, voffB); PG8_STAGE(PG8_SA(0, 0), cA, voffA); PG8_STAGE(PG8_SB(0, 1), cB + hstepB, voffB); PG8_STAGE(PG8_SA(0, 1), cA + hstepA, voffA);
;     if (wr == 1) PG8_BAR;
;     PG8_WAIT_V(4); PG8_BAR;
;     PG8_STAGE(PG8_SB(1, 0), cB + kstep, voffB); PG8_STAGE(PG8_SA(1, 0), cA + kstep, voffA); PG8_STAGE(PG8_SB(1, 1), cB + hstepB + kstep, voffB);
;     PG8_WAIT_V(6); PG8_BAR;
.LBB0_1388:
	v_lshl_add_u64 v[10:11], s[20:21], 0, v[2:3]
	v_mov_b32_e32 v193, v3
	v_readlane_b32 s6, v254, 5
	s_lshl_b32 s0, s0, 5
	v_lshl_add_u64 v[12:13], s[20:21], 0, v[192:193]
	v_mov_b32_e32 v197, v3
	v_readlane_b32 s7, v254, 6
	v_and_b32_e32 v18, 48, v1
	v_lshlrev_b32_e32 v19, 6, v1
	s_movk_i32 s4, 0x3c0
	v_lshlrev_b32_e32 v1, 2, v1
	s_and_b32 s39, s0, 0x60
	s_add_i32 m0, s31, 0x18000
	v_lshl_add_u64 v[10:11], v[10:11], 0, s[8:9]
	v_lshl_add_u64 v[14:15], s[6:7], 0, v[196:197]
	v_mov_b32_e32 v195, v3
	s_lshl_b32 s38, s1, 6
	s_lshl_b32 s1, s1, 13
	v_and_or_b32 v18, v19, s4, v18
	v_and_b32_e32 v1, 32, v1
	s_lshl_b32 s0, s39, 7
	s_waitcnt vmcnt(2)
	s_barrier
	global_load_lds_dwordx4 v[10:11], off
	v_lshl_add_u64 v[10:11], v[12:13], 0, s[8:9]
	s_add_i32 m0, s31, 0x1a000
	s_add_i32 s42, s31, 0x8000
	s_add_i32 s43, s31, 0xa000
	v_lshl_add_u64 v[16:17], s[6:7], 0, v[194:195]
	v_bitop3_b32 v19, v18, s1, v1 bitop3:0xde
	v_bitop3_b32 v1, s0, v18, v1 bitop3:0xf6
	global_load_lds_dwordx4 v[10:11], off
	v_lshl_add_u64 v[10:11], v[14:15], 0, s[8:9]
	s_mov_b32 m0, s42
	s_add_u32 s0, s20, 0x80080
	global_load_lds_dwordx4 v[10:11], off
	v_lshl_add_u64 v[10:11], v[16:17], 0, s[8:9]
	s_mov_b32 m0, s43
	s_addc_u32 s1, s21, 0
	global_load_lds_dwordx4 v[10:11], off
	s_add_i32 m0, s31, 0x1c000
	v_lshl_add_u64 v[10:11], s[0:1], 0, v[2:3]
	global_load_lds_dwordx4 v[10:11], off
	v_lshl_add_u64 v[10:11], s[0:1], 0, v[192:193]
	s_add_i32 m0, s31, 0x1e000
	v_readlane_b32 s0, v254, 27
	global_load_lds_dwordx4 v[10:11], off
	v_lshlrev_b32_e32 v10, 15, v8
	v_and_b32_e32 v10, 0xffff0000, v10
	v_lshl_add_u32 v7, v7, 12, v10
	v_and_b32_e32 v8, 1, v8
	v_lshl_or_b32 v7, v8, 6, v7
	v_lshl_add_u32 v198, v9, 1, v7
	v_lshlrev_b32_e32 v7, 15, v4
	v_and_b32_e32 v7, 0xffff0000, v7
	s_waitcnt vmcnt(6)
	v_lshl_add_u32 v5, v5, 12, v7
	v_and_b32_e32 v4, 1, v4
	v_lshl_or_b32 v4, v4, 6, v5
	v_mov_b32_e32 v199, v3
	v_lshl_add_u32 v200, v6, 1, v4
	v_mov_b32_e32 v201, v3
	s_mov_b32 s44, 0
	v_add_u32_e32 v224, 0, v19
	v_readlane_b32 s45, v254, 1
	s_mov_b32 s46, s0
	s_barrier
	v_readlane_b32 s1, v254, 28

; #define PG8_STAGE(bufoff, gbase, voff) do { _Pragma("unroll") for (int _i = 0; _i < 2; ++_i) \
;         __builtin_amdgcn_global_load_lds((const unsigned*)((const char*)(gbase) + (voff)[_i]), (LAS unsigned*)(lds + (bufoff) + ldsw + _i * 8192), 16, 0, 0); } while (0)
; #define PG8_LDA(dst, b, h) do { _Pragma("unroll") for (int m = 0; m < 4; ++m) _Pragma("unroll") for (int k = 0; k < 2; ++k) dst[m][k] = *(const LAS bf16x8*)(lds + PG8_SA(b, h) + aoff + m * 2048 + k * 1024); } while (0)
; #define PG8_LDB(dst, b, h) do { _Pragma("unroll") for (int n = 0; n < 2; ++n) _Pragma("unroll") for (int k = 0; k < 2; ++k) dst[n][k] = *(const LAS bf16x8*)(lds + PG8_SB(b, h) + boff + n * 2048 + k * 1024); } while (0)
; #define PG8_MMA(ai, bj, At, Bt) do { __builtin_amdgcn_s_setprio(1); _Pragma("unroll") for (int m = 0; m < 4; ++m) _Pragma("unroll") for (int n = 0; n < 2; ++n) _Pragma("unroll") for (int k = 0; k < 2; ++k) \
;         acc[ai][bj][m][n] = __builtin_amdgcn_mfma_f32_16x16x32_bf16(Bt[n][k], At[m][k], acc[ai][bj][m][n], 0, 0, 0); __builtin_amdgcn_s_setprio(0); } while (0)
; #define PG8_WAIT_V(n) asm volatile("s_waitcnt vmcnt(" #n ")" ::: "memory")
; #define PG8_WAIT_L(n) asm volatile("s_waitcnt lgkmcnt(" #n ")" ::: "memory")
; template <class Epi, class Sched>
; __device__ __forceinline__ void gemm_phase(LAS unsigned char* lds, const Gemm g, const Sched& S, const Epi& E) {
;     ...
;             const bool last = (t == nt - 2);
;             const char* a1 = cA + (size_t)(t + 1) * kstep;
;             const char* a2 = last ? nA : cA + (size_t)(t + 2) * kstep; const char* b2 = last ? nB : cB + (size_t)(t + 2) * kstep;
;             const char* a3 = a2 + kstep; const char* b3 = b2 + kstep;
;             if (last && has_next) S.a_ready(nxt);
;             PG8_LDB(B0, 0, 0); PG8_SCHED; PG8_LDA(At, 0, 0); PG8_STAGE(PG8_SA(1, 1), a1 + hstepA, voffA);
;             PG8_WAIT_L(8); PG8_BAR; PG8_WAIT_L(0); PG8_MMA(0, 0, At, B0); PG8_BAR; PG8_SCHED;
;             PG8_LDB(B1, 0, 1); PG8_STAGE(PG8_SB(0, 0), b2, voffB);
;             PG8_BAR; PG8_WAIT_L(0); PG8_MMA(0, 1, At, B1); PG8_BAR;
;             PG8_LDA(At, 0, 1); PG8_STAGE(PG8_SA(0, 0), a2, voffA);
;             PG8_BAR; PG8_WAIT_L(0); PG8_MMA(1, 0, At, B0); PG8_BAR; PG8_SCHED;
;             PG8_STAGE(PG8_SB(0, 1), b2 + hstepB, voffB);
;             PG8_WAIT_V(6); PG8_BAR; PG8_MMA(1, 1, At, B1); PG8_BAR;
.LBB0_1396:
	s_add_u32 s20, s6, 0xfff80080
	s_addc_u32 s21, s7, -1
	s_add_i32 s52, 0, 0x10000
	v_add_u32_e32 v144, s52, v1
	ds_read_b128 v[132:135], v144
	ds_read_b128 v[136:139], v144 offset:1024
	ds_read_b128 v[140:143], v144 offset:2048
	ds_read_b128 v[144:147], v144 offset:3072
	s_cmp_eq_u32 s51, 28
	s_cselect_b32 s25, s15, s21
	s_cselect_b32 s24, s47, s20
	s_cselect_b32 s21, s1, s50
	s_cselect_b32 s20, s48, s49
	s_add_i32 m0, s31, 0xc000
	ds_read_b128 v[148:151], v224
	ds_read_b128 v[152:155], v224 offset:1024
	ds_read_b128 v[156:159], v224 offset:2048
	ds_read_b128 v[160:163], v224 offset:3072
	ds_read_b128 v[164:167], v224 offset:4096
	ds_read_b128 v[168:171], v224 offset:5120
	ds_read_b128 v[172:175], v224 offset:6144
	ds_read_b128 v[176:179], v224 offset:7168
	s_add_i32 s54, 0, 0x14000
	v_add_u32_e32 v202, s54, v1
	ds_read_b128 v[180:183], v202
	ds_read_b128 v[184:187], v202 offset:1024
	ds_read_b128 v[188:191], v202 offset:2048
	ds_read_b128 v[202:205], v202 offset:3072
	s_add_i32 m0, s31, 0xc000
	s_nop 0
	global_load_lds_dwordx4 v198, s[6:7]
	s_add_i32 m0, s31, 0xe000
	s_nop 0
	global_load_lds_dwordx4 v200, s[6:7]
	s_waitcnt lgkmcnt(0)
	s_barrier
	s_setprio 1
	v_mfma_f32_16x16x32_bf16 v[128:131], v[132:135], v[148:151], v[128:131]
	v_mfma_f32_16x16x32_bf16 v[124:127], v[140:143], v[148:151], v[124:127]
	v_mfma_f32_16x16x32_bf16 v[112:115], v[132:135], v[156:159], v[112:115]
	v_mfma_f32_16x16x32_bf16 v[108:111], v[140:143], v[156:159], v[108:111]
	v_mfma_f32_16x16x32_bf16 v[100:103], v[132:135], v[164:167], v[100:103]
	v_mfma_f32_16x16x32_bf16 v[92:95], v[140:143], v[164:167], v[92:95]
	v_mfma_f32_16x16x32_bf16 v[84:87], v[132:135], v[172:175], v[84:87]
	v_mfma_f32_16x16x32_bf16 v[76:79], v[140:143], v[172:175], v[76:79]
	v_mfma_f32_16x16x32_bf16 v[128:131], v[136:139], v[152:155], v[128:131]
	v_mfma_f32_16x16x32_bf16 v[124:127], v[144:147], v[152:155], v[124:127]
	v_mfma_f32_16x16x32_bf16 v[112:115], v[136:139], v[160:163], v[112:115]
	v_mfma_f32_16x16x32_bf16 v[108:111], v[144:147], v[160:163], v[108:111]
	v_mfma_f32_16x16x32_bf16 v[100:103], v[136:139], v[168:171], v[100:103]
	v_mfma_f32_16x16x32_bf16 v[92:95], v[144:147], v[168:171], v[92:95]
	v_mfma_f32_16x16x32_bf16 v[84:87], v[136:139], v[176:179], v[84:87]
	v_mfma_f32_16x16x32_bf16 v[76:79], v[144:147], v[176:179], v[76:79]
	v_mfma_f32_16x16x32_bf16 v[120:123], v[180:183], v[148:151], v[120:123]
	v_mfma_f32_16x16x32_bf16 v[116:119], v[188:191], v[148:151], v[116:119]
	v_mfma_f32_16x16x32_bf16 v[104:107], v[180:183], v[156:159], v[104:107]
	v_mfma_f32_16x16x32_bf16 v[96:99], v[188:191], v[156:159], v[96:99]
	v_mfma_f32_16x16x32_bf16 v[88:91], v[180:183], v[164:167], v[88:91]
	v_mfma_f32_16x16x32_bf16 v[80:83], v[188:191], v[164:167], v[80:83]
	v_mfma_f32_16x16x32_bf16 v[72:75], v[180:183], v[172:175], v[72:75]
	v_mfma_f32_16x16x32_bf16 v[68:71], v[188:191], v[172:175], v[68:71]
	v_mfma_f32_16x16x32_bf16 v[120:123], v[184:187], v[152:155], v[120:123]
	v_mfma_f32_16x16x32_bf16 v[116:119], v[202:205], v[152:155], v[116:119]
	v_mfma_f32_16x16x32_bf16 v[104:107], v[184:187], v[160:163], v[104:107]
	v_mfma_f32_16x16x32_bf16 v[96:99], v[202:205], v[160:163], v[96:99]
	v_mfma_f32_16x16x32_bf16 v[88:91], v[184:187], v[168:171], v[88:91]
	v_mfma_f32_16x16x32_bf16 v[80:83], v[202:205], v[168:171], v[80:83]
	v_mfma_f32_16x16x32_bf16 v[72:75], v[184:187], v[176:179], v[72:75]
	v_mfma_f32_16x16x32_bf16 v[68:71], v[202:205], v[176:179], v[68:71]
	s_setprio 0
	s_barrier
	ds_read_b128 v[148:151], v224 offset:16384
	ds_read_b128 v[152:155], v224 offset:17408
	ds_read_b128 v[156:159], v224 offset:18432
	ds_read_b128 v[160:163], v224 offset:19456
	ds_read_b128 v[164:167], v224 offset:20480
	ds_read_b128 v[168:171], v224 offset:21504
	ds_read_b128 v[172:175], v224 offset:22528
	ds_read_b128 v[176:179], v224 offset:23552
	s_add_i32 s52, s52, s30
	v_lshl_add_u64 v[206:207], s[20:21], 0, v[2:3]
	s_mov_b32 m0, s52
	s_nop 0
	global_load_lds_dwordx4 v[206:207], off
	v_lshl_add_u64 v[208:209], s[20:21], 0, v[192:193]
	s_add_i32 m0, s52, 0x2000
	s_nop 0
	global_load_lds_dwordx4 v[208:209], off
	s_mov_b32 m0, s31
	v_lshl_add_u64 v[210:211], s[24:25], 0, v[196:197]
	s_nop 0
	global_load_lds_dwordx4 v[210:211], off
	v_lshl_add_u64 v[212:213], s[24:25], 0, v[194:195]
	s_mov_b32 m0, s35
	s_nop 0
	global_load_lds_dwordx4 v[212:213], off
	s_add_u32 s52, s20, 0x80000
	s_addc_u32 s53, s21, 0
	s_add_i32 s54, s54, s30
	s_mov_b32 m0, s54
	s_nop 0
	global_load_lds_dwordx4 v2, s[52:53]
	s_add_i32 m0, s54, 0x2000
	s_nop 0
	global_load_lds_dwordx4 v192, s[52:53]
	s_waitcnt lgkmcnt(0)
	s_waitcnt vmcnt(6)
	s_barrier
; #define PG8_STAGE(bufoff, gbase, voff) do { _Pragma("unroll") for (int _i = 0; _i < 2; ++_i) \
;         __builtin_amdgcn_global_load_lds((const unsigned*)((const char*)(gbase) + (voff)[_i]), (LAS unsigned*)(lds + (bufoff) + ldsw + _i * 8192), 16, 0, 0); } while (0)
; #define PG8_LDA(dst, b, h) do { _Pragma("unroll") for (int m = 0; m < 4; ++m) _Pragma("unroll") for (int k = 0; k < 2; ++k) dst[m][k] = *(const LAS bf16x8*)(lds + PG8_SA(b, h) + aoff + m * 2048 + k * 1024); } while (0)
; #define PG8_LDB(dst, b, h) do { _Pragma("unroll") for (int n = 0; n < 2; ++n) _Pragma("unroll") for (int k = 0; k < 2; ++k) dst[n][k] = *(const LAS bf16x8*)(lds + PG8_SB(b, h) + boff + n * 2048 + k * 1024); } while (0)
; #define PG8_MMA(ai, bj, At, Bt) do { __builtin_amdgcn_s_setprio(1); _Pragma("unroll") for (int m = 0; m < 4; ++m) _Pragma("unroll") for (int n = 0; n < 2; ++n) _Pragma("unroll") for (int k = 0; k < 2; ++k) \
;         acc[ai][bj][m][n] = __builtin_amdgcn_mfma_f32_16x16x32_bf16(Bt[n][k], At[m][k], acc[ai][bj][m][n], 0, 0, 0); __builtin_amdgcn_s_setprio(0); } while (0)
; #define PG8_WAIT_V(n) asm volatile("s_waitcnt vmcnt(" #n ")" ::: "memory")
; #define PG8_WAIT_L(n) asm volatile("s_waitcnt lgkmcnt(" #n ")" ::: "memory")
; #define PG8_BAR __builtin_amdgcn_s_barrier()
; #define PG8_SCHED __builtin_amdgcn_sched_barrier(0)
; template <class Epi, class Sched>
; __device__ __forceinline__ void gemm_phase(LAS unsigned char* lds, const Gemm g, const Sched& S, const Epi& E) {
;     ...
;             PG8_BAR; PG8_WAIT_L(0); PG8_MMA(1, 0, At, B0); PG8_BAR; PG8_SCHED;
;             PG8_STAGE(PG8_SB(0, 1), b2 + hstepB, voffB);
;             PG8_WAIT_V(6); PG8_BAR; PG8_MMA(1, 1, At, B1); PG8_BAR;
;             PG8_LDB(B0, 1, 0); PG8_SCHED; PG8_LDA(At, 1, 0); PG8_STAGE(PG8_SA(0, 1), a2 + hstepA, voffA);
;             PG8_WAIT_L(8); PG8_BAR; PG8_WAIT_L(0); PG8_MMA(0, 0, At, B0); PG8_BAR; PG8_SCHED;
;             PG8_LDB(B1, 1, 1); PG8_STAGE(PG8_SB(1, 0), b3, voffB);
;             PG8_BAR; PG8_WAIT_L(0); PG8_MMA(0, 1, At, B1); PG8_BAR;
;             PG8_LDA(At, 1, 1); PG8_STAGE(PG8_SA(1, 0), a3, voffA);
;             PG8_BAR; PG8_WAIT_L(0); PG8_MMA(1, 0, At, B0); PG8_BAR; PG8_SCHED;
	s_setprio 1
	v_mfma_f32_16x16x32_bf16 v[64:67], v[132:135], v[148:151], v[64:67]
	v_mfma_f32_16x16x32_bf16 v[60:63], v[140:143], v[148:151], v[60:63]
	v_mfma_f32_16x16x32_bf16 v[52:55], v[132:135], v[156:159], v[52:55]
	v_mfma_f32_16x16x32_bf16 v[44:47], v[140:143], v[156:159], v[44:47]
	v_mfma_f32_16x16x32_bf16 v[36:39], v[132:135], v[164:167], v[36:39]
	v_mfma_f32_16x16x32_bf16 v[28:31], v[140:143], v[164:167], v[28:31]
	v_mfma_f32_16x16x32_bf16 v[20:23], v[132:135], v[172:175], v[20:23]
	v_mfma_f32_16x16x32_bf16 v[12:15], v[140:143], v[172:175], v[12:15]
	v_mfma_f32_16x16x32_bf16 v[64:67], v[136:139], v[152:155], v[64:67]
	v_mfma_f32_16x16x32_bf16 v[60:63], v[144:147], v[152:155], v[60:63]
	v_mfma_f32_16x16x32_bf16 v[52:55], v[136:139], v[160:163], v[52:55]
	v_mfma_f32_16x16x32_bf16 v[44:47], v[144:147], v[160:163], v[44:47]
	v_mfma_f32_16x16x32_bf16 v[36:39], v[136:139], v[168:171], v[36:39]
	v_mfma_f32_16x16x32_bf16 v[28:31], v[144:147], v[168:171], v[28:31]
	v_mfma_f32_16x16x32_bf16 v[20:23], v[136:139], v[176:179], v[20:23]
	v_mfma_f32_16x16x32_bf16 v[12:15], v[144:147], v[176:179], v[12:15]
	v_mfma_f32_16x16x32_bf16 v[56:59], v[180:183], v[148:151], v[56:59]
	v_mfma_f32_16x16x32_bf16 v[48:51], v[188:191], v[148:151], v[48:51]
	v_mfma_f32_16x16x32_bf16 v[40:43], v[180:183], v[156:159], v[40:43]
	v_mfma_f32_16x16x32_bf16 v[32:35], v[188:191], v[156:159], v[32:35]
	v_mfma_f32_16x16x32_bf16 v[24:27], v[180:183], v[164:167], v[24:27]
	v_mfma_f32_16x16x32_bf16 v[16:19], v[188:191], v[164:167], v[16:19]
	v_mfma_f32_16x16x32_bf16 v[8:11], v[180:183], v[172:175], v[8:11]
	v_mfma_f32_16x16x32_bf16 v[4:7], v[188:191], v[172:175], v[4:7]
	v_mfma_f32_16x16x32_bf16 v[56:59], v[184:187], v[152:155], v[56:59]
	v_mfma_f32_16x16x32_bf16 v[48:51], v[202:205], v[152:155], v[48:51]
	v_mfma_f32_16x16x32_bf16 v[40:43], v[184:187], v[160:163], v[40:43]
	v_mfma_f32_16x16x32_bf16 v[32:35], v[202:205], v[160:163], v[32:35]
	v_mfma_f32_16x16x32_bf16 v[24:27], v[184:187], v[168:171], v[24:27]
	v_mfma_f32_16x16x32_bf16 v[16:19], v[202:205], v[168:171], v[16:19]
	v_mfma_f32_16x16x32_bf16 v[8:11], v[184:187], v[176:179], v[8:11]
	v_mfma_f32_16x16x32_bf16 v[4:7], v[202:205], v[176:179], v[4:7]
	s_setprio 0
	s_add_i32 s52, 0, 0x18000
	v_add_u32_e32 v144, s52, v1
	s_barrier
	ds_read_b128 v[132:135], v144
	ds_read_b128 v[136:139], v144 offset:1024
	ds_read_b128 v[140:143], v144 offset:2048
	ds_read_b128 v[144:147], v144 offset:3072
	s_add_u32 s24, s24, 0x80000
	s_addc_u32 s25, s25, 0
	s_mov_b32 m0, s36
	ds_read_b128 v[148:151], v224 offset:32768
	ds_read_b128 v[152:155], v224 offset:33792
	ds_read_b128 v[156:159], v224 offset:34816
	ds_read_b128 v[160:163], v224 offset:35840
	ds_read_b128 v[164:167], v224 offset:36864
	ds_read_b128 v[168:171], v224 offset:37888
	ds_read_b128 v[172:175], v224 offset:38912
	ds_read_b128 v[176:179], v224 offset:39936
	global_load_lds_dwordx4 v196, s[24:25]
	s_mov_b32 m0, s37
	s_nop 0
	global_load_lds_dwordx4 v194, s[24:25]
	s_add_i32 s24, 0, 0x1c000
	v_add_u32_e32 v202, s24, v1
	ds_read_b128 v[180:183], v202
	ds_read_b128 v[184:187], v202 offset:1024
	ds_read_b128 v[188:191], v202 offset:2048
	ds_read_b128 v[202:205], v202 offset:3072
	s_waitcnt lgkmcnt(0)
	s_barrier
	s_setprio 1
	v_mfma_f32_16x16x32_bf16 v[128:131], v[132:135], v[148:151], v[128:131]
	v_mfma_f32_16x16x32_bf16 v[124:127], v[140:143], v[148:151], v[124:127]
	v_mfma_f32_16x16x32_bf16 v[112:115], v[132:135], v[156:159], v[112:115]
	v_mfma_f32_16x16x32_bf16 v[108:111], v[140:143], v[156:159], v[108:111]
	v_mfma_f32_16x16x32_bf16 v[100:103], v[132:135], v[164:167], v[100:103]
	v_mfma_f32_16x16x32_bf16 v[92:95], v[140:143], v[164:167], v[92:95]
	v_mfma_f32_16x16x32_bf16 v[84:87], v[132:135], v[172:175], v[84:87]
	v_mfma_f32_16x16x32_bf16 v[76:79], v[140:143], v[172:175], v[76:79]
	v_mfma_f32_16x16x32_bf16 v[128:131], v[136:139], v[152:155], v[128:131]
	v_mfma_f32_16x16x32_bf16 v[124:127], v[144:147], v[152:155], v[124:127]
	v_mfma_f32_16x16x32_bf16 v[112:115], v[136:139], v[160:163], v[112:115]
	v_mfma_f32_16x16x32_bf16 v[108:111], v[144:147], v[160:163], v[108:111]
	v_mfma_f32_16x16x32_bf16 v[100:103], v[136:139], v[168:171], v[100:103]
	v_mfma_f32_16x16x32_bf16 v[92:95], v[144:147], v[168:171], v[92:95]
	v_mfma_f32_16x16x32_bf16 v[84:87], v[136:139], v[176:179], v[84:87]
	v_mfma_f32_16x16x32_bf16 v[76:79], v[144:147], v[176:179], v[76:79]
	v_mfma_f32_16x16x32_bf16 v[120:123], v[180:183], v[148:151], v[120:123]
	v_mfma_f32_16x16x32_bf16 v[116:119], v[188:191], v[148:151], v[116:119]
	v_mfma_f32_16x16x32_bf16 v[104:107], v[180:183], v[156:159], v[104:107]
	v_mfma_f32_16x16x32_bf16 v[96:99], v[188:191], v[156:159], v[96:99]
	v_mfma_f32_16x16x32_bf16 v[88:91], v[180:183], v[164:167], v[88:91]
	v_mfma_f32_16x16x32_bf16 v[80:83], v[188:191], v[164:167], v[80:83]
	v_mfma_f32_16x16x32_bf16 v[72:75], v[180:183], v[172:175], v[72:75]
	v_mfma_f32_16x16x32_bf16 v[68:71], v[188:191], v[172:175], v[68:71]
	v_mfma_f32_16x16x32_bf16 v[120:123], v[184:187], v[152:155], v[120:123]
	v_mfma_f32_16x16x32_bf16 v[116:119], v[202:205], v[152:155], v[116:119]
	v_mfma_f32_16x16x32_bf16 v[104:107], v[184:187], v[160:163], v[104:107]
	v_mfma_f32_16x16x32_bf16 v[96:99], v[202:205], v[160:163], v[96:99]
	v_mfma_f32_16x16x32_bf16 v[88:91], v[184:187], v[168:171], v[88:91]
	v_mfma_f32_16x16x32_bf16 v[80:83], v[202:205], v[168:171], v[80:83]
	v_mfma_f32_16x16x32_bf16 v[72:75], v[184:187], v[176:179], v[72:75]
	v_mfma_f32_16x16x32_bf16 v[68:71], v[202:205], v[176:179], v[68:71]
	s_setprio 0
	s_barrier
; __device__ __forceinline__ int opaque_tid() { int t = threadIdx.x; asm volatile("" : "+v"(t)); return t; }
; #define PG8_STAGE(bufoff, gbase, voff) do { _Pragma("unroll") for (int _i = 0; _i < 2; ++_i) \
;         __builtin_amdgcn_global_load_lds((const unsigned*)((const char*)(gbase) + (voff)[_i]), (LAS unsigned*)(lds + (bufoff) + ldsw + _i * 8192), 16, 0, 0); } while (0)
; #define PG8_LDA(dst, b, h) do { _Pragma("unroll") for (int m = 0; m < 4; ++m) _Pragma("unroll") for (int k = 0; k < 2; ++k) dst[m][k] = *(const LAS bf16x8*)(lds + PG8_SA(b, h) + aoff + m * 2048 + k * 1024); } while (0)
; #define PG8_MMA(ai, bj, At, Bt) do { __builtin_amdgcn_s_setprio(1); _Pragma("unroll") for (int m = 0; m < 4; ++m) _Pragma("unroll") for (int n = 0; n < 2; ++n) _Pragma("unroll") for (int k = 0; k < 2; ++k) \
;         acc[ai][bj][m][n] = __builtin_amdgcn_mfma_f32_16x16x32_bf16(Bt[n][k], At[m][k], acc[ai][bj][m][n], 0, 0, 0); __builtin_amdgcn_s_setprio(0); } while (0)
; #define PG8_WAIT_V(n) asm volatile("s_waitcnt vmcnt(" #n ")" ::: "memory")
; #define PG8_WAIT_L(n) asm volatile("s_waitcnt lgkmcnt(" #n ")" ::: "memory")
; #define PG8_BAR __builtin_amdgcn_s_barrier()
; #define PG8_SCHED __builtin_amdgcn_sched_barrier(0)
;     __device__ __forceinline__ void operator()(const f32x4 (&acc)[2][2][4][2], const Unit& u, int wr, int wc, int, int) const {
;         const int ol_ = opaque_tid() & 63, fr = ol_ & 15, fq = ol_ >> 4;
;         const int row0 = u.pm * BM + wr * 64 + fr, col0 = u.pn * BM + wc * 32 + 8 * fq;
;         u32x4 cin[2][4][2];
; #pragma unroll
;         for (int ai = 0; ai < 2; ++ai)
; #pragma unroll
;             for (int m = 0; m < 4; ++m)
; #pragma unroll
;                 for (int bj = 0; bj < 2; ++bj) cin[ai][m][bj] = *(const u32x4*)(C + (size_t)(row0 + ai * HALF + m * 16) * ldc + col0 + bj * HALF);
; template <class Epi, class Sched>
; __device__ __forceinline__ void gemm_phase(LAS unsigned char* lds, const Gemm g, const Sched& S, const Epi& E) {
;     ...
;             PG8_LDA(At, 1, 1); PG8_STAGE(PG8_SA(1, 0), a3, voffA);
;             PG8_BAR; PG8_WAIT_L(0); PG8_MMA(1, 0, At, B0); PG8_BAR; PG8_SCHED;
;             PG8_STAGE(PG8_SB(1, 1), b3 + hstepB, voffB);
;             PG8_WAIT_V(6); PG8_BAR; PG8_MMA(1, 1, At, B1); PG8_BAR;
	ds_read_b128 v[148:151], v224 offset:49152
	ds_read_b128 v[152:155], v224 offset:50176
	ds_read_b128 v[156:159], v224 offset:51200
	ds_read_b128 v[160:163], v224 offset:52224
	ds_read_b128 v[164:167], v224 offset:53248
	ds_read_b128 v[168:171], v224 offset:54272
	ds_read_b128 v[172:175], v224 offset:55296
	ds_read_b128 v[176:179], v224 offset:56320
	s_add_i32 s25, s52, s30
	v_lshl_add_u64 v[206:207], v[206:207], 0, s[8:9]
	s_mov_b32 m0, s25
	s_nop 0
	global_load_lds_dwordx4 v[206:207], off
	v_lshl_add_u64 v[206:207], v[208:209], 0, s[8:9]
	s_add_i32 m0, s25, 0x2000
	s_nop 0
	global_load_lds_dwordx4 v[206:207], off
	s_mov_b32 m0, s42
	v_lshl_add_u64 v[206:207], v[210:211], 0, s[8:9]
	s_nop 0
	global_load_lds_dwordx4 v[206:207], off
	v_lshl_add_u64 v[206:207], v[212:213], 0, s[8:9]
	s_mov_b32 m0, s43
	s_nop 0
	global_load_lds_dwordx4 v[206:207], off
	s_add_u32 s20, s20, 0x80080
	s_addc_u32 s21, s21, 0
	s_add_i32 s24, s24, s30
	s_mov_b32 m0, s24
	s_nop 0
	global_load_lds_dwordx4 v2, s[20:21]
	s_add_i32 m0, s24, 0x2000
	s_nop 0
	global_load_lds_dwordx4 v192, s[20:21]
	s_waitcnt lgkmcnt(0)
	s_waitcnt vmcnt(6)
	s_barrier
	s_setprio 1
	v_mfma_f32_16x16x32_bf16 v[64:67], v[132:135], v[148:151], v[64:67]
	v_mfma_f32_16x16x32_bf16 v[60:63], v[140:143], v[148:151], v[60:63]
	v_mfma_f32_16x16x32_bf16 v[52:55], v[132:135], v[156:159], v[52:55]
	v_mfma_f32_16x16x32_bf16 v[44:47], v[140:143], v[156:159], v[44:47]
	v_mfma_f32_16x16x32_bf16 v[36:39], v[132:135], v[164:167], v[36:39]
	v_mfma_f32_16x16x32_bf16 v[28:31], v[140:143], v[164:167], v[28:31]
	v_mfma_f32_16x16x32_bf16 v[20:23], v[132:135], v[172:175], v[20:23]
	v_mfma_f32_16x16x32_bf16 v[12:15], v[140:143], v[172:175], v[12:15]
	v_mfma_f32_16x16x32_bf16 v[64:67], v[136:139], v[152:155], v[64:67]
	v_mfma_f32_16x16x32_bf16 v[60:63], v[144:147], v[152:155], v[60:63]
	v_mfma_f32_16x16x32_bf16 v[52:55], v[136:139], v[160:163], v[52:55]
	v_mfma_f32_16x16x32_bf16 v[44:47], v[144:147], v[160:163], v[44:47]
	v_mfma_f32_16x16x32_bf16 v[36:39], v[136:139], v[168:171], v[36:39]
	v_mfma_f32_16x16x32_bf16 v[28:31], v[144:147], v[168:171], v[28:31]
	v_mfma_f32_16x16x32_bf16 v[20:23], v[136:139], v[176:179], v[20:23]
	v_mfma_f32_16x16x32_bf16 v[12:15], v[144:147], v[176:179], v[12:15]
	v_mfma_f32_16x16x32_bf16 v[56:59], v[180:183], v[148:151], v[56:59]
	v_mfma_f32_16x16x32_bf16 v[48:51], v[188:191], v[148:151], v[48:51]
	v_mfma_f32_16x16x32_bf16 v[40:43], v[180:183], v[156:159], v[40:43]
	v_mfma_f32_16x16x32_bf16 v[32:35], v[188:191], v[156:159], v[32:35]
	v_mfma_f32_16x16x32_bf16 v[24:27], v[180:183], v[164:167], v[24:27]
	v_mfma_f32_16x16x32_bf16 v[16:19], v[188:191], v[164:167], v[16:19]
	v_mfma_f32_16x16x32_bf16 v[8:11], v[180:183], v[172:175], v[8:11]
	v_mfma_f32_16x16x32_bf16 v[4:7], v[188:191], v[172:175], v[4:7]
	v_mfma_f32_16x16x32_bf16 v[56:59], v[184:187], v[152:155], v[56:59]
	v_mfma_f32_16x16x32_bf16 v[48:51], v[202:205], v[152:155], v[48:51]
	v_mfma_f32_16x16x32_bf16 v[40:43], v[184:187], v[160:163], v[40:43]
	v_mfma_f32_16x16x32_bf16 v[32:35], v[202:205], v[160:163], v[32:35]
	v_mfma_f32_16x16x32_bf16 v[24:27], v[184:187], v[168:171], v[24:27]
	v_mfma_f32_16x16x32_bf16 v[16:19], v[202:205], v[168:171], v[16:19]
	v_mfma_f32_16x16x32_bf16 v[8:11], v[184:187], v[176:179], v[8:11]
	v_mfma_f32_16x16x32_bf16 v[4:7], v[202:205], v[176:179], v[4:7]
	s_setprio 0
	s_add_i32 s51, s51, 2
	s_add_u32 s6, s6, 0x100
	s_addc_u32 s7, s7, 0
	s_add_u32 s49, s49, 0x100
	s_addc_u32 s50, s50, 0
	s_cmp_gt_u32 s51, 29
	s_barrier
	s_cbranch_scc0 .LBB0_1396
	v_mov_b32_e32 v133, v0
	s_lshl_b32 s1, s46, 8
	s_add_i32 s1, s1, s38
	v_and_or_b32 v132, v133, 15, s1
	s_lshl_b32 s1, s45, 8
	v_lshrrev_b32_e32 v133, 1, v133
	v_and_or_b32 v133, v133, 24, s1
	v_or_b32_e32 v134, s39, v133
	v_ashrrev_i32_e32 v135, 31, v134
	v_lshlrev_b64 v[202:203], 1, v[134:135]
	v_ashrrev_i32_e32 v133, 31, v132
	v_lshl_add_u64 v[134:135], s[88:89], 0, v[202:203]
	v_lshlrev_b64 v[216:217], 12, v[132:133]
	v_lshl_add_u64 v[136:137], v[134:135], 0, v[216:217]
	global_load_dwordx4 v[226:229], v[136:137], off
	global_load_dwordx4 v[188:191], v[136:137], off offset:256
	v_or_b32_e32 v136, 16, v132
	v_ashrrev_i32_e32 v137, 31, v136
	v_lshlrev_b64 v[222:223], 12, v[136:137]
	v_lshl_add_u64 v[136:137], v[134:135], 0, v[222:223]
	global_load_dwordx4 v[184:187], v[136:137], off
	global_load_dwordx4 v[180:183], v[136:137], off offset:256
	v_or_b32_e32 v136, 32, v132
	v_ashrrev_i32_e32 v137, 31, v136
	v_lshlrev_b64 v[220:221], 12, v[136:137]
	v_lshl_add_u64 v[136:137], v[134:135], 0, v[220:221]
	global_load_dwordx4 v[176:179], v[136:137], off
	global_load_dwordx4 v[168:171], v[136:137], off offset:256
	v_or_b32_e32 v132, 48, v132
	v_ashrrev_i32_e32 v133, 31, v132
	v_lshlrev_b64 v[212:213], 12, v[132:133]
	v_lshl_add_u64 v[132:133], v[134:135], 0, v[212:213]
	global_load_dwordx4 v[172:175], v[132:133], off
	global_load_dwordx4 v[164:167], v[132:133], off offset:256
	s_mov_b64 s[6:7], 0x80000
	v_lshl_add_u64 v[210:211], v[216:217], 0, s[6:7]
	v_lshl_add_u64 v[132:133], v[134:135], 0, v[210:211]
	global_load_dwordx4 v[160:163], v[132:133], off
	global_load_dwordx4 v[156:159], v[132:133], off offset:256
	s_mov_b64 s[6:7], 0x90000
	v_lshl_add_u64 v[208:209], v[216:217], 0, s[6:7]
	v_lshl_add_u64 v[132:133], v[134:135], 0, v[208:209]
	global_load_dwordx4 v[152:155], v[132:133], off
	global_load_dwordx4 v[148:151], v[132:133], off offset:256
	s_mov_b64 s[6:7], 0xa0000
	v_lshl_add_u64 v[206:207], v[216:217], 0, s[6:7]
	v_lshl_add_u64 v[132:133], v[134:135], 0, v[206:207]
	global_load_dwordx4 v[144:147], v[132:133], off
	global_load_dwordx4 v[140:143], v[132:133], off offset:256
	s_mov_b64 s[6:7], 0xb0000
	v_lshl_add_u64 v[204:205], v[216:217], 0, s[6:7]
	v_lshl_add_u64 v[132:133], v[134:135], 0, v[204:205]
	global_load_dwordx4 v[136:139], v[132:133], off
	s_nop 0
	global_load_dwordx4 v[132:135], v[132:133], off offset:256
	s_and_b64 vcc, exec, s[40:41]
	s_mov_b32 s45, s0
	s_mov_b32 s46, s14
	s_mov_b64 s[20:21], s[18:19]
	s_mov_b64 s[6:7], s[4:5]
	s_waitcnt vmcnt(0)
; __device__ __forceinline__ unsigned cvt_pk_bf16(float lo, float hi) { const f32x2 v = {lo, hi}; const bf16v2_ r = __builtin_convertvector(v, bf16v2_); return __builtin_bit_cast(unsigned, r); }
; __device__ __forceinline__ float bflo(unsigned w) { return __uint_as_float(w << 16); }
; __device__ __forceinline__ float bfhi(unsigned w) { return __uint_as_float(w & 0xffff0000u); }
;     __device__ __forceinline__ void operator()(const f32x4 (&acc)[2][2][4][2], const Unit& u, int wr, int wc, int, int) const {
;     ...
; #pragma unroll
;         for (int ai = 0; ai < 2; ++ai)
; #pragma unroll
;             for (int m = 0; m < 4; ++m)
; #pragma unroll
;                 for (int bj = 0; bj < 2; ++bj) { const u32x4 c = cin[ai][m][bj]; const f32x4 v0 = acc[ai][bj][m][0], v1 = acc[ai][bj][m][1];
;                     u32x4 w; w.x = cvt_pk_bf16(bflo(c.x) + v0[0], bfhi(c.x) + v0[1]); w.y = cvt_pk_bf16(bflo(c.y) + v0[2], bfhi(c.y) + v0[3]);
;                     w.z = cvt_pk_bf16(bflo(c.z) + v1[0], bfhi(c.z) + v1[1]); w.w = cvt_pk_bf16(bflo(c.w) + v1[2], bfhi(c.w) + v1[3]);
;                     *(u32x4*)(C + (size_t)(row0 + ai * HALF + m * 16) * ldc + col0 + bj * HALF) = w; }
	v_lshlrev_b32_e32 v218, 16, v226
	v_and_b32_e32 v219, 0xffff0000, v226
	v_pk_add_f32 v[128:129], v[128:129], v[218:219]
	v_lshlrev_b32_e32 v218, 16, v227
	v_and_b32_e32 v219, 0xffff0000, v227
	v_pk_add_f32 v[130:131], v[130:131], v[218:219]
	v_cvt_pk_bf16_f32 v128, v128, v129
	v_cvt_pk_bf16_f32 v129, v130, v131
	v_lshlrev_b32_e32 v130, 16, v228
	v_and_b32_e32 v131, 0xffff0000, v228
	v_pk_add_f32 v[124:125], v[124:125], v[130:131]
	s_nop 0
	v_cvt_pk_bf16_f32 v130, v124, v125
	v_lshlrev_b32_e32 v124, 16, v229
	v_and_b32_e32 v125, 0xffff0000, v229
	v_pk_add_f32 v[124:125], v[126:127], v[124:125]
	v_lshlrev_b32_e32 v126, 16, v188
	v_and_b32_e32 v127, 0xffff0000, v188
	v_pk_add_f32 v[120:121], v[120:121], v[126:127]
	v_lshlrev_b32_e32 v126, 16, v189
	v_and_b32_e32 v127, 0xffff0000, v189
	v_pk_add_f32 v[122:123], v[122:123], v[126:127]
	v_cvt_pk_bf16_f32 v120, v120, v121
	v_cvt_pk_bf16_f32 v121, v122, v123
	v_lshlrev_b32_e32 v122, 16, v190
	v_and_b32_e32 v123, 0xffff0000, v190
	v_pk_add_f32 v[116:117], v[116:117], v[122:123]
	v_cvt_pk_bf16_f32 v131, v124, v125
	v_cvt_pk_bf16_f32 v122, v116, v117
	v_lshlrev_b32_e32 v116, 16, v191
	v_and_b32_e32 v117, 0xffff0000, v191
	v_pk_add_f32 v[116:117], v[118:119], v[116:117]
	v_lshl_add_u64 v[124:125], s[88:89], 0, v[216:217]
	v_cvt_pk_bf16_f32 v123, v116, v117
	v_lshlrev_b32_e32 v116, 16, v184
	v_and_b32_e32 v117, 0xffff0000, v184
	v_pk_add_f32 v[112:113], v[112:113], v[116:117]
	v_lshlrev_b32_e32 v116, 16, v185
	v_and_b32_e32 v117, 0xffff0000, v185
	v_pk_add_f32 v[114:115], v[114:115], v[116:117]
	v_cvt_pk_bf16_f32 v112, v112, v113
	v_cvt_pk_bf16_f32 v113, v114, v115
	v_lshlrev_b32_e32 v114, 16, v186
	v_and_b32_e32 v115, 0xffff0000, v186
	v_pk_add_f32 v[108:109], v[108:109], v[114:115]
	v_lshl_add_u64 v[124:125], v[124:125], 0, v[202:203]
	v_cvt_pk_bf16_f32 v114, v108, v109
	v_lshlrev_b32_e32 v108, 16, v187
	v_and_b32_e32 v109, 0xffff0000, v187
	v_pk_add_f32 v[108:109], v[110:111], v[108:109]
	v_lshlrev_b32_e32 v110, 16, v180
	v_and_b32_e32 v111, 0xffff0000, v180
	v_pk_add_f32 v[104:105], v[104:105], v[110:111]
	v_lshlrev_b32_e32 v110, 16, v181
	v_and_b32_e32 v111, 0xffff0000, v181
	v_pk_add_f32 v[106:107], v[106:107], v[110:111]
	v_cvt_pk_bf16_f32 v104, v104, v105
	v_cvt_pk_bf16_f32 v105, v106, v107
	v_lshlrev_b32_e32 v106, 16, v182
	v_and_b32_e32 v107, 0xffff0000, v182
	v_pk_add_f32 v[96:97], v[96:97], v[106:107]
	v_cvt_pk_bf16_f32 v115, v108, v109
	v_cvt_pk_bf16_f32 v106, v96, v97
	v_lshlrev_b32_e32 v96, 16, v183
	v_and_b32_e32 v97, 0xffff0000, v183
	v_pk_add_f32 v[96:97], v[98:99], v[96:97]
	v_lshlrev_b32_e32 v98, 16, v177
	v_cvt_pk_bf16_f32 v107, v96, v97
	v_lshlrev_b32_e32 v96, 16, v176
	v_and_b32_e32 v97, 0xffff0000, v176
	v_and_b32_e32 v99, 0xffff0000, v177
	v_pk_add_f32 v[96:97], v[100:101], v[96:97]
	v_pk_add_f32 v[98:99], v[102:103], v[98:99]
	v_cvt_pk_bf16_f32 v96, v96, v97
	v_cvt_pk_bf16_f32 v97, v98, v99
	v_lshlrev_b32_e32 v98, 16, v178
	v_and_b32_e32 v99, 0xffff0000, v178
	v_pk_add_f32 v[92:93], v[92:93], v[98:99]
	v_lshl_add_u64 v[108:109], s[88:89], 0, v[222:223]
	v_cvt_pk_bf16_f32 v98, v92, v93
	v_lshlrev_b32_e32 v92, 16, v179
	v_and_b32_e32 v93, 0xffff0000, v179
	v_pk_add_f32 v[92:93], v[94:95], v[92:93]
	v_lshlrev_b32_e32 v94, 16, v168
	v_and_b32_e32 v95, 0xffff0000, v168
	v_pk_add_f32 v[88:89], v[88:89], v[94:95]
	v_lshlrev_b32_e32 v94, 16, v169
	v_and_b32_e32 v95, 0xffff0000, v169
	v_pk_add_f32 v[90:91], v[90:91], v[94:95]
	v_cvt_pk_bf16_f32 v88, v88, v89
	v_cvt_pk_bf16_f32 v89, v90, v91
	v_lshlrev_b32_e32 v90, 16, v170
	v_and_b32_e32 v91, 0xffff0000, v170
	v_pk_add_f32 v[80:81], v[80:81], v[90:91]
	v_cvt_pk_bf16_f32 v99, v92, v93
	v_cvt_pk_bf16_f32 v90, v80, v81
	v_lshlrev_b32_e32 v80, 16, v171
	v_and_b32_e32 v81, 0xffff0000, v171
	v_pk_add_f32 v[80:81], v[82:83], v[80:81]
	v_lshlrev_b32_e32 v82, 16, v173
	v_cvt_pk_bf16_f32 v91, v80, v81
	v_lshlrev_b32_e32 v80, 16, v172
	v_and_b32_e32 v81, 0xffff0000, v172
	v_and_b32_e32 v83, 0xffff0000, v173
	v_pk_add_f32 v[80:81], v[84:85], v[80:81]
	v_pk_add_f32 v[82:83], v[86:87], v[82:83]
	v_cvt_pk_bf16_f32 v80, v80, v81
	v_cvt_pk_bf16_f32 v81, v82, v83
	v_lshlrev_b32_e32 v82, 16, v174
	v_and_b32_e32 v83, 0xffff0000, v174
	v_pk_add_f32 v[76:77], v[76:77], v[82:83]
	v_lshl_add_u64 v[92:93], s[88:89], 0, v[220:221]
	v_cvt_pk_bf16_f32 v82, v76, v77
	v_lshlrev_b32_e32 v76, 16, v175
	v_and_b32_e32 v77, 0xffff0000, v175
	v_pk_add_f32 v[76:77], v[78:79], v[76:77]
	v_lshlrev_b32_e32 v78, 16, v164
	v_and_b32_e32 v79, 0xffff0000, v164
	v_pk_add_f32 v[72:73], v[72:73], v[78:79]
	v_lshlrev_b32_e32 v78, 16, v165
	v_and_b32_e32 v79, 0xffff0000, v165
	v_pk_add_f32 v[74:75], v[74:75], v[78:79]
	v_cvt_pk_bf16_f32 v72, v72, v73
	v_cvt_pk_bf16_f32 v73, v74, v75
	v_lshlrev_b32_e32 v74, 16, v166
	v_and_b32_e32 v75, 0xffff0000, v166
	v_pk_add_f32 v[68:69], v[68:69], v[74:75]
	v_cvt_pk_bf16_f32 v83, v76, v77
	v_cvt_pk_bf16_f32 v74, v68, v69
	v_lshlrev_b32_e32 v68, 16, v167
	v_and_b32_e32 v69, 0xffff0000, v167
	v_pk_add_f32 v[68:69], v[70:71], v[68:69]
	v_lshl_add_u64 v[76:77], s[88:89], 0, v[212:213]
	v_cvt_pk_bf16_f32 v75, v68, v69
	v_lshlrev_b32_e32 v68, 16, v160
	v_and_b32_e32 v69, 0xffff0000, v160
	v_pk_add_f32 v[64:65], v[64:65], v[68:69]
	v_lshlrev_b32_e32 v68, 16, v161
	v_and_b32_e32 v69, 0xffff0000, v161
	v_pk_add_f32 v[66:67], v[66:67], v[68:69]
	v_cvt_pk_bf16_f32 v64, v64, v65
	v_cvt_pk_bf16_f32 v65, v66, v67
	v_lshlrev_b32_e32 v66, 16, v162
	v_and_b32_e32 v67, 0xffff0000, v162
	v_pk_add_f32 v[60:61], v[60:61], v[66:67]
	v_lshl_add_u64 v[108:109], v[108:109], 0, v[202:203]
	v_cvt_pk_bf16_f32 v66, v60, v61
	v_lshlrev_b32_e32 v60, 16, v163
; __device__ __forceinline__ unsigned cvt_pk_bf16(float lo, float hi) { const f32x2 v = {lo, hi}; const bf16v2_ r = __builtin_convertvector(v, bf16v2_); return __builtin_bit_cast(unsigned, r); }
; __device__ __forceinline__ float bflo(unsigned w) { return __uint_as_float(w << 16); }
; __device__ __forceinline__ float bfhi(unsigned w) { return __uint_as_float(w & 0xffff0000u); }
;     __device__ __forceinline__ void operator()(const f32x4 (&acc)[2][2][4][2], const Unit& u, int wr, int wc, int, int) const {
;     ...
; #pragma unroll
;         for (int ai = 0; ai < 2; ++ai)
; #pragma unroll
;             for (int m = 0; m < 4; ++m)
; #pragma unroll
;                 for (int bj = 0; bj < 2; ++bj) { const u32x4 c = cin[ai][m][bj]; const f32x4 v0 = acc[ai][bj][m][0], v1 = acc[ai][bj][m][1];
;                     u32x4 w; w.x = cvt_pk_bf16(bflo(c.x) + v0[0], bfhi(c.x) + v0[1]); w.y = cvt_pk_bf16(bflo(c.y) + v0[2], bfhi(c.y) + v0[3]);
;                     w.z = cvt_pk_bf16(bflo(c.z) + v1[0], bfhi(c.z) + v1[1]); w.w = cvt_pk_bf16(bflo(c.w) + v1[2], bfhi(c.w) + v1[3]);
;                     *(u32x4*)(C + (size_t)(row0 + ai * HALF + m * 16) * ldc + col0 + bj * HALF) = w; }
	v_and_b32_e32 v61, 0xffff0000, v163
	v_pk_add_f32 v[60:61], v[62:63], v[60:61]
	v_lshlrev_b32_e32 v62, 16, v156
	v_and_b32_e32 v63, 0xffff0000, v156
	v_pk_add_f32 v[56:57], v[56:57], v[62:63]
	v_lshlrev_b32_e32 v62, 16, v157
	v_and_b32_e32 v63, 0xffff0000, v157
	v_pk_add_f32 v[58:59], v[58:59], v[62:63]
	v_cvt_pk_bf16_f32 v56, v56, v57
	v_cvt_pk_bf16_f32 v57, v58, v59
	v_lshlrev_b32_e32 v58, 16, v158
	v_and_b32_e32 v59, 0xffff0000, v158
	v_pk_add_f32 v[48:49], v[48:49], v[58:59]
	v_cvt_pk_bf16_f32 v67, v60, v61
	v_cvt_pk_bf16_f32 v58, v48, v49
	v_lshlrev_b32_e32 v48, 16, v159
	v_and_b32_e32 v49, 0xffff0000, v159
	v_pk_add_f32 v[48:49], v[50:51], v[48:49]
	v_lshlrev_b32_e32 v50, 16, v153
	v_cvt_pk_bf16_f32 v59, v48, v49
	v_lshlrev_b32_e32 v48, 16, v152
	v_and_b32_e32 v49, 0xffff0000, v152
	v_and_b32_e32 v51, 0xffff0000, v153
	v_pk_add_f32 v[48:49], v[52:53], v[48:49]
	v_pk_add_f32 v[50:51], v[54:55], v[50:51]
	v_cvt_pk_bf16_f32 v48, v48, v49
	v_cvt_pk_bf16_f32 v49, v50, v51
	v_lshlrev_b32_e32 v50, 16, v154
	v_and_b32_e32 v51, 0xffff0000, v154
	v_pk_add_f32 v[44:45], v[44:45], v[50:51]
	v_lshl_add_u64 v[60:61], s[88:89], 0, v[210:211]
	v_cvt_pk_bf16_f32 v50, v44, v45
	v_lshlrev_b32_e32 v44, 16, v155
	v_and_b32_e32 v45, 0xffff0000, v155
	v_pk_add_f32 v[44:45], v[46:47], v[44:45]
	v_lshlrev_b32_e32 v46, 16, v148
	v_and_b32_e32 v47, 0xffff0000, v148
	v_pk_add_f32 v[40:41], v[40:41], v[46:47]
	v_lshlrev_b32_e32 v46, 16, v149
	v_and_b32_e32 v47, 0xffff0000, v149
	v_pk_add_f32 v[42:43], v[42:43], v[46:47]
	v_cvt_pk_bf16_f32 v40, v40, v41
	v_cvt_pk_bf16_f32 v41, v42, v43
	v_lshlrev_b32_e32 v42, 16, v150
	v_and_b32_e32 v43, 0xffff0000, v150
	v_pk_add_f32 v[32:33], v[32:33], v[42:43]
	v_cvt_pk_bf16_f32 v51, v44, v45
	v_cvt_pk_bf16_f32 v42, v32, v33
	v_lshlrev_b32_e32 v32, 16, v151
	v_and_b32_e32 v33, 0xffff0000, v151
	v_pk_add_f32 v[32:33], v[34:35], v[32:33]
	v_lshlrev_b32_e32 v34, 16, v145
	v_cvt_pk_bf16_f32 v43, v32, v33
	v_lshlrev_b32_e32 v32, 16, v144
	v_and_b32_e32 v33, 0xffff0000, v144
	v_and_b32_e32 v35, 0xffff0000, v145
	v_pk_add_f32 v[32:33], v[36:37], v[32:33]
	v_pk_add_f32 v[34:35], v[38:39], v[34:35]
	v_cvt_pk_bf16_f32 v32, v32, v33
	v_cvt_pk_bf16_f32 v33, v34, v35
	v_lshlrev_b32_e32 v34, 16, v146
	v_and_b32_e32 v35, 0xffff0000, v146
	v_pk_add_f32 v[28:29], v[28:29], v[34:35]
	v_lshl_add_u64 v[44:45], s[88:89], 0, v[208:209]
	v_cvt_pk_bf16_f32 v34, v28, v29
	v_lshlrev_b32_e32 v28, 16, v147
	v_and_b32_e32 v29, 0xffff0000, v147
	v_pk_add_f32 v[28:29], v[30:31], v[28:29]
	v_lshlrev_b32_e32 v30, 16, v140
	v_and_b32_e32 v31, 0xffff0000, v140
	v_pk_add_f32 v[24:25], v[24:25], v[30:31]
	v_lshlrev_b32_e32 v30, 16, v141
	v_and_b32_e32 v31, 0xffff0000, v141
	v_pk_add_f32 v[26:27], v[26:27], v[30:31]
	v_cvt_pk_bf16_f32 v24, v24, v25
	v_cvt_pk_bf16_f32 v25, v26, v27
	v_lshlrev_b32_e32 v26, 16, v142
	v_and_b32_e32 v27, 0xffff0000, v142
	v_pk_add_f32 v[16:17], v[16:17], v[26:27]
	v_cvt_pk_bf16_f32 v35, v28, v29
	v_cvt_pk_bf16_f32 v26, v16, v17
	v_lshlrev_b32_e32 v16, 16, v143
	v_and_b32_e32 v17, 0xffff0000, v143
	v_pk_add_f32 v[16:17], v[18:19], v[16:17]
	v_lshlrev_b32_e32 v18, 16, v137
	v_cvt_pk_bf16_f32 v27, v16, v17
	v_lshlrev_b32_e32 v16, 16, v136
	v_and_b32_e32 v17, 0xffff0000, v136
	v_and_b32_e32 v19, 0xffff0000, v137
	v_pk_add_f32 v[16:17], v[20:21], v[16:17]
	v_pk_add_f32 v[18:19], v[22:23], v[18:19]
	v_cvt_pk_bf16_f32 v16, v16, v17
	v_cvt_pk_bf16_f32 v17, v18, v19
	v_lshlrev_b32_e32 v18, 16, v138
	v_and_b32_e32 v19, 0xffff0000, v138
	v_pk_add_f32 v[12:13], v[12:13], v[18:19]
	v_lshl_add_u64 v[28:29], s[88:89], 0, v[206:207]
	v_cvt_pk_bf16_f32 v18, v12, v13
	v_lshlrev_b32_e32 v12, 16, v139
	v_and_b32_e32 v13, 0xffff0000, v139
	v_pk_add_f32 v[12:13], v[14:15], v[12:13]
	v_lshlrev_b32_e32 v14, 16, v132
	v_and_b32_e32 v15, 0xffff0000, v132
	v_pk_add_f32 v[8:9], v[8:9], v[14:15]
	v_lshlrev_b32_e32 v14, 16, v133
	v_and_b32_e32 v15, 0xffff0000, v133
	v_pk_add_f32 v[10:11], v[10:11], v[14:15]
	v_cvt_pk_bf16_f32 v8, v8, v9
	v_cvt_pk_bf16_f32 v9, v10, v11
	v_lshlrev_b32_e32 v10, 16, v134
	v_and_b32_e32 v11, 0xffff0000, v134
	v_pk_add_f32 v[4:5], v[4:5], v[10:11]
	v_cvt_pk_bf16_f32 v19, v12, v13
	v_cvt_pk_bf16_f32 v10, v4, v5
	v_lshlrev_b32_e32 v4, 16, v135
	v_and_b32_e32 v5, 0xffff0000, v135
	v_lshl_add_u64 v[12:13], s[88:89], 0, v[204:205]
	v_pk_add_f32 v[4:5], v[6:7], v[4:5]
	v_lshl_add_u64 v[92:93], v[92:93], 0, v[202:203]
	v_lshl_add_u64 v[76:77], v[76:77], 0, v[202:203]
	v_lshl_add_u64 v[60:61], v[60:61], 0, v[202:203]
	v_lshl_add_u64 v[44:45], v[44:45], 0, v[202:203]
	v_lshl_add_u64 v[28:29], v[28:29], 0, v[202:203]
	v_lshl_add_u64 v[12:13], v[12:13], 0, v[202:203]
	v_cvt_pk_bf16_f32 v11, v4, v5
	global_store_dwordx4 v[124:125], v[128:131], off
	global_store_dwordx4 v[124:125], v[120:123], off offset:256
	global_store_dwordx4 v[108:109], v[112:115], off
	global_store_dwordx4 v[108:109], v[104:107], off offset:256
	global_store_dwordx4 v[92:93], v[96:99], off
	global_store_dwordx4 v[92:93], v[88:91], off offset:256
	global_store_dwordx4 v[76:77], v[80:83], off
	global_store_dwordx4 v[76:77], v[72:75], off offset:256
	global_store_dwordx4 v[60:61], v[64:67], off
	global_store_dwordx4 v[60:61], v[56:59], off offset:256
	global_store_dwordx4 v[44:45], v[48:51], off
	global_store_dwordx4 v[44:45], v[40:43], off offset:256
	global_store_dwordx4 v[28:29], v[32:35], off
	global_store_dwordx4 v[28:29], v[24:27], off offset:256
	global_store_dwordx4 v[12:13], v[16:19], off
	global_store_dwordx4 v[12:13], v[8:11], off offset:256
	s_cbranch_vccz .LBB0_1389
	s_waitcnt vmcnt(0)
	s_cmpk_gt_u32 s2, 0xff
	s_cbranch_scc1 .LBB0_1400
	s_barrier

; #define PG8_STAGE(bufoff, gbase, voff) do { _Pragma("unroll") for (int _i = 0; _i < 2; ++_i) \
;         __builtin_amdgcn_global_load_lds((const unsigned*)((const char*)(gbase) + (voff)[_i]), (LAS unsigned*)(lds + (bufoff) + ldsw + _i * 8192), 16, 0, 0); } while (0)
; #define PG8_LDA(dst, b, h) do { _Pragma("unroll") for (int m = 0; m < 4; ++m) _Pragma("unroll") for (int k = 0; k < 2; ++k) dst[m][k] = *(const LAS bf16x8*)(lds + PG8_SA(b, h) + aoff + m * 2048 + k * 1024); } while (0)
; #define PG8_LDB(dst, b, h) do { _Pragma("unroll") for (int n = 0; n < 2; ++n) _Pragma("unroll") for (int k = 0; k < 2; ++k) dst[n][k] = *(const LAS bf16x8*)(lds + PG8_SB(b, h) + boff + n * 2048 + k * 1024); } while (0)
; #define PG8_WAIT_V(n) asm volatile("s_waitcnt vmcnt(" #n ")" ::: "memory")
; #define PG8_WAIT_L(n) asm volatile("s_waitcnt lgkmcnt(" #n ")" ::: "memory")
; #define PG8_BAR __builtin_amdgcn_s_barrier()
; #define PG8_SCHED __builtin_amdgcn_sched_barrier(0)
; template <class Epi, class Sched>
; __device__ __forceinline__ void gemm_phase(LAS unsigned char* lds, const Gemm g, const Sched& S, const Epi& E) {
;     ...
;             const bool last = (t == nt - 2);
;             const char* a1 = cA + (size_t)(t + 1) * kstep;
;             const char* a2 = last ? nA : cA + (size_t)(t + 2) * kstep; const char* b2 = last ? nB : cB + (size_t)(t + 2) * kstep;
;             const char* a3 = a2 + kstep; const char* b3 = b2 + kstep;
;             if (last && has_next) S.a_ready(nxt);
;             PG8_LDB(B0, 0, 0); PG8_SCHED; PG8_LDA(At, 0, 0); PG8_STAGE(PG8_SA(1, 1), a1 + hstepA, voffA);
;             PG8_WAIT_L(8); PG8_BAR; PG8_WAIT_L(0); PG8_MMA(0, 0, At, B0); PG8_BAR; PG8_SCHED;
;             PG8_LDB(B1, 0, 1); PG8_STAGE(PG8_SB(0, 0), b2, voffB);
;             PG8_BAR; PG8_WAIT_L(0); PG8_MMA(0, 1, At, B1); PG8_BAR;
;             PG8_LDA(At, 0, 1); PG8_STAGE(PG8_SA(0, 0), a2, voffA);
;             PG8_BAR; PG8_WAIT_L(0); PG8_MMA(1, 0, At, B0); PG8_BAR; PG8_SCHED;
;             PG8_STAGE(PG8_SB(0, 1), b2 + hstepB, voffB);
;             PG8_WAIT_V(6); PG8_BAR; PG8_MMA(1, 1, At, B1); PG8_BAR;
;             PG8_LDB(B0, 1, 0); PG8_SCHED; PG8_LDA(At, 1, 0); PG8_STAGE(PG8_SA(0, 1), a2 + hstepA, voffA);
;             PG8_WAIT_L(8); PG8_BAR; PG8_WAIT_L(0); PG8_MMA(0, 0, At, B0); PG8_BAR; PG8_SCHED;
.LBB0_1526:
	s_add_u32 s6, s4, 0xfff80080
	s_addc_u32 s7, s5, -1
	s_add_i32 s72, 0, 0x10000
	v_add_u32_e32 v2, s72, v1
	ds_read_b128 v[132:135], v2
	ds_read_b128 v[136:139], v2 offset:1024
	ds_read_b128 v[140:143], v2 offset:2048
	ds_read_b128 v[144:147], v2 offset:3072
	s_cmp_eq_u32 s71, 28
	s_cselect_b32 s15, s57, s7
	s_cselect_b32 s14, s67, s6
	s_cselect_b32 s7, s55, s70
	s_cselect_b32 s6, s68, s69
	s_add_i32 m0, s20, 0xc000
	ds_read_b128 v[148:151], v207
	ds_read_b128 v[152:155], v207 offset:1024
	ds_read_b128 v[156:159], v207 offset:2048
	ds_read_b128 v[160:163], v207 offset:3072
	ds_read_b128 v[164:167], v207 offset:4096
	ds_read_b128 v[168:171], v207 offset:5120
	ds_read_b128 v[186:189], v207 offset:6144
	ds_read_b128 v[190:193], v207 offset:7168
	s_add_i32 s74, 0, 0x14000
	v_add_u32_e32 v2, s74, v1
	ds_read_b128 v[194:197], v2
	ds_read_b128 v[198:201], v2 offset:1024
	ds_read_b128 v[202:205], v2 offset:2048
	ds_read_b128 v[208:211], v2 offset:3072
	s_add_i32 m0, s20, 0xc000
	s_nop 0
	global_load_lds_dwordx4 v182, s[4:5]
	s_add_i32 m0, s20, 0xe000
	s_nop 0
	global_load_lds_dwordx4 v184, s[4:5]
	s_waitcnt lgkmcnt(0)
	s_barrier
	s_setprio 1
	v_mfma_f32_16x16x32_bf16 v[68:71], v[132:135], v[148:151], v[68:71]
	v_mfma_f32_16x16x32_bf16 v[72:75], v[140:143], v[148:151], v[72:75]
	v_mfma_f32_16x16x32_bf16 v[120:123], v[132:135], v[156:159], v[120:123]
	v_mfma_f32_16x16x32_bf16 v[116:119], v[140:143], v[156:159], v[116:119]
	v_mfma_f32_16x16x32_bf16 v[112:115], v[132:135], v[164:167], v[112:115]
	v_mfma_f32_16x16x32_bf16 v[108:111], v[140:143], v[164:167], v[108:111]
	v_mfma_f32_16x16x32_bf16 v[104:107], v[132:135], v[186:189], v[104:107]
	v_mfma_f32_16x16x32_bf16 v[100:103], v[140:143], v[186:189], v[100:103]
	v_mfma_f32_16x16x32_bf16 v[68:71], v[136:139], v[152:155], v[68:71]
	v_mfma_f32_16x16x32_bf16 v[72:75], v[144:147], v[152:155], v[72:75]
	v_mfma_f32_16x16x32_bf16 v[120:123], v[136:139], v[160:163], v[120:123]
	v_mfma_f32_16x16x32_bf16 v[116:119], v[144:147], v[160:163], v[116:119]
	v_mfma_f32_16x16x32_bf16 v[112:115], v[136:139], v[168:171], v[112:115]
	v_mfma_f32_16x16x32_bf16 v[108:111], v[144:147], v[168:171], v[108:111]
	v_mfma_f32_16x16x32_bf16 v[104:107], v[136:139], v[190:193], v[104:107]
	v_mfma_f32_16x16x32_bf16 v[100:103], v[144:147], v[190:193], v[100:103]
	v_mfma_f32_16x16x32_bf16 v[76:79], v[194:197], v[148:151], v[76:79]
	v_mfma_f32_16x16x32_bf16 v[80:83], v[202:205], v[148:151], v[80:83]
	v_mfma_f32_16x16x32_bf16 v[96:99], v[194:197], v[156:159], v[96:99]
	v_mfma_f32_16x16x32_bf16 v[92:95], v[202:205], v[156:159], v[92:95]
	v_mfma_f32_16x16x32_bf16 v[88:91], v[194:197], v[164:167], v[88:91]
	v_mfma_f32_16x16x32_bf16 v[84:87], v[202:205], v[164:167], v[84:87]
	v_mfma_f32_16x16x32_bf16 v[128:131], v[194:197], v[186:189], v[128:131]
	v_mfma_f32_16x16x32_bf16 v[124:127], v[202:205], v[186:189], v[124:127]
	v_mfma_f32_16x16x32_bf16 v[76:79], v[198:201], v[152:155], v[76:79]
	v_mfma_f32_16x16x32_bf16 v[80:83], v[208:211], v[152:155], v[80:83]
	v_mfma_f32_16x16x32_bf16 v[96:99], v[198:201], v[160:163], v[96:99]
	v_mfma_f32_16x16x32_bf16 v[92:95], v[208:211], v[160:163], v[92:95]
	v_mfma_f32_16x16x32_bf16 v[88:91], v[198:201], v[168:171], v[88:91]
	v_mfma_f32_16x16x32_bf16 v[84:87], v[208:211], v[168:171], v[84:87]
	v_mfma_f32_16x16x32_bf16 v[128:131], v[198:201], v[190:193], v[128:131]
	v_mfma_f32_16x16x32_bf16 v[124:127], v[208:211], v[190:193], v[124:127]
	s_setprio 0
	s_barrier
	ds_read_b128 v[148:151], v207 offset:16384
	ds_read_b128 v[152:155], v207 offset:17408
	ds_read_b128 v[156:159], v207 offset:18432
	ds_read_b128 v[160:163], v207 offset:19456
	ds_read_b128 v[164:167], v207 offset:20480
	ds_read_b128 v[168:171], v207 offset:21504
	ds_read_b128 v[186:189], v207 offset:22528
	ds_read_b128 v[190:193], v207 offset:23552
	s_add_i32 s72, s72, s19
	v_lshl_add_u64 v[172:173], s[6:7], 0, v[178:179]
	s_mov_b32 m0, s72
	s_nop 0
	global_load_lds_dwordx4 v[172:173], off
	v_lshl_add_u64 v[212:213], s[6:7], 0, v[174:175]
	s_add_i32 m0, s72, 0x2000
	s_nop 0
	global_load_lds_dwordx4 v[212:213], off
	s_mov_b32 m0, s20
	v_lshl_add_u64 v[216:217], s[14:15], 0, v[180:181]
	s_nop 0
	global_load_lds_dwordx4 v[216:217], off
	v_lshl_add_u64 v[218:219], s[14:15], 0, v[176:177]
	s_mov_b32 m0, s21
	s_nop 0
	global_load_lds_dwordx4 v[218:219], off
	s_add_u32 s72, s6, 0x80000
	s_addc_u32 s73, s7, 0
	s_add_i32 s74, s74, s19
	s_mov_b32 m0, s74
	s_nop 0
	global_load_lds_dwordx4 v178, s[72:73]
	s_add_i32 m0, s74, 0x2000
	s_nop 0
	global_load_lds_dwordx4 v174, s[72:73]
	s_waitcnt lgkmcnt(0)
	s_waitcnt vmcnt(6)
	s_barrier
; #define PG8_STAGE(bufoff, gbase, voff) do { _Pragma("unroll") for (int _i = 0; _i < 2; ++_i) \
;         __builtin_amdgcn_global_load_lds((const unsigned*)((const char*)(gbase) + (voff)[_i]), (LAS unsigned*)(lds + (bufoff) + ldsw + _i * 8192), 16, 0, 0); } while (0)
; #define PG8_LDA(dst, b, h) do { _Pragma("unroll") for (int m = 0; m < 4; ++m) _Pragma("unroll") for (int k = 0; k < 2; ++k) dst[m][k] = *(const LAS bf16x8*)(lds + PG8_SA(b, h) + aoff + m * 2048 + k * 1024); } while (0)
; #define PG8_LDB(dst, b, h) do { _Pragma("unroll") for (int n = 0; n < 2; ++n) _Pragma("unroll") for (int k = 0; k < 2; ++k) dst[n][k] = *(const LAS bf16x8*)(lds + PG8_SB(b, h) + boff + n * 2048 + k * 1024); } while (0)
; #define PG8_MMA(ai, bj, At, Bt) do { __builtin_amdgcn_s_setprio(1); _Pragma("unroll") for (int m = 0; m < 4; ++m) _Pragma("unroll") for (int n = 0; n < 2; ++n) _Pragma("unroll") for (int k = 0; k < 2; ++k) \
;         acc[ai][bj][m][n] = __builtin_amdgcn_mfma_f32_16x16x32_bf16(Bt[n][k], At[m][k], acc[ai][bj][m][n], 0, 0, 0); __builtin_amdgcn_s_setprio(0); } while (0)
; #define PG8_WAIT_V(n) asm volatile("s_waitcnt vmcnt(" #n ")" ::: "memory")
; #define PG8_WAIT_L(n) asm volatile("s_waitcnt lgkmcnt(" #n ")" ::: "memory")
; #define PG8_BAR __builtin_amdgcn_s_barrier()
; #define PG8_SCHED __builtin_amdgcn_sched_barrier(0)
; template <class Epi, class Sched>
; __device__ __forceinline__ void gemm_phase(LAS unsigned char* lds, const Gemm g, const Sched& S, const Epi& E) {
;     ...
;             PG8_WAIT_V(6); PG8_BAR; PG8_MMA(1, 1, At, B1); PG8_BAR;
;             PG8_LDB(B0, 1, 0); PG8_SCHED; PG8_LDA(At, 1, 0); PG8_STAGE(PG8_SA(0, 1), a2 + hstepA, voffA);
;             PG8_WAIT_L(8); PG8_BAR; PG8_WAIT_L(0); PG8_MMA(0, 0, At, B0); PG8_BAR; PG8_SCHED;
;             PG8_LDB(B1, 1, 1); PG8_STAGE(PG8_SB(1, 0), b3, voffB);
;             PG8_BAR; PG8_WAIT_L(0); PG8_MMA(0, 1, At, B1); PG8_BAR;
;             PG8_LDA(At, 1, 1); PG8_STAGE(PG8_SA(1, 0), a3, voffA);
;             PG8_BAR; PG8_WAIT_L(0); PG8_MMA(1, 0, At, B0); PG8_BAR; PG8_SCHED;
	s_setprio 1
	v_mfma_f32_16x16x32_bf16 v[56:59], v[132:135], v[148:151], v[56:59]
	v_mfma_f32_16x16x32_bf16 v[52:55], v[140:143], v[148:151], v[52:55]
	v_mfma_f32_16x16x32_bf16 v[48:51], v[132:135], v[156:159], v[48:51]
	v_mfma_f32_16x16x32_bf16 v[44:47], v[140:143], v[156:159], v[44:47]
	v_mfma_f32_16x16x32_bf16 v[40:43], v[132:135], v[164:167], v[40:43]
	v_mfma_f32_16x16x32_bf16 v[36:39], v[140:143], v[164:167], v[36:39]
	v_mfma_f32_16x16x32_bf16 v[32:35], v[132:135], v[186:189], v[32:35]
	v_mfma_f32_16x16x32_bf16 v[28:31], v[140:143], v[186:189], v[28:31]
	v_mfma_f32_16x16x32_bf16 v[56:59], v[136:139], v[152:155], v[56:59]
	v_mfma_f32_16x16x32_bf16 v[52:55], v[144:147], v[152:155], v[52:55]
	v_mfma_f32_16x16x32_bf16 v[48:51], v[136:139], v[160:163], v[48:51]
	v_mfma_f32_16x16x32_bf16 v[44:47], v[144:147], v[160:163], v[44:47]
	v_mfma_f32_16x16x32_bf16 v[40:43], v[136:139], v[168:171], v[40:43]
	v_mfma_f32_16x16x32_bf16 v[36:39], v[144:147], v[168:171], v[36:39]
	v_mfma_f32_16x16x32_bf16 v[32:35], v[136:139], v[190:193], v[32:35]
	v_mfma_f32_16x16x32_bf16 v[28:31], v[144:147], v[190:193], v[28:31]
	v_mfma_f32_16x16x32_bf16 v[24:27], v[194:197], v[148:151], v[24:27]
	v_mfma_f32_16x16x32_bf16 v[20:23], v[202:205], v[148:151], v[20:23]
	v_mfma_f32_16x16x32_bf16 v[16:19], v[194:197], v[156:159], v[16:19]
	v_mfma_f32_16x16x32_bf16 v[12:15], v[202:205], v[156:159], v[12:15]
	v_mfma_f32_16x16x32_bf16 v[8:11], v[194:197], v[164:167], v[8:11]
	v_mfma_f32_16x16x32_bf16 v[4:7], v[202:205], v[164:167], v[4:7]
	v_mfma_f32_16x16x32_bf16 v[60:63], v[194:197], v[186:189], v[60:63]
	v_mfma_f32_16x16x32_bf16 v[64:67], v[202:205], v[186:189], v[64:67]
	v_mfma_f32_16x16x32_bf16 v[24:27], v[198:201], v[152:155], v[24:27]
	v_mfma_f32_16x16x32_bf16 v[20:23], v[208:211], v[152:155], v[20:23]
	v_mfma_f32_16x16x32_bf16 v[16:19], v[198:201], v[160:163], v[16:19]
	v_mfma_f32_16x16x32_bf16 v[12:15], v[208:211], v[160:163], v[12:15]
	v_mfma_f32_16x16x32_bf16 v[8:11], v[198:201], v[168:171], v[8:11]
	v_mfma_f32_16x16x32_bf16 v[4:7], v[208:211], v[168:171], v[4:7]
	v_mfma_f32_16x16x32_bf16 v[60:63], v[198:201], v[190:193], v[60:63]
	v_mfma_f32_16x16x32_bf16 v[64:67], v[208:211], v[190:193], v[64:67]
	s_setprio 0
	s_add_i32 s72, 0, 0x18000
	v_add_u32_e32 v2, s72, v1
	s_barrier
	ds_read_b128 v[132:135], v2
	ds_read_b128 v[136:139], v2 offset:1024
	ds_read_b128 v[140:143], v2 offset:2048
	ds_read_b128 v[144:147], v2 offset:3072
	s_add_u32 s14, s14, 0x80000
	s_addc_u32 s15, s15, 0
	s_mov_b32 m0, s24
	ds_read_b128 v[148:151], v207 offset:32768
	ds_read_b128 v[152:155], v207 offset:33792
	ds_read_b128 v[156:159], v207 offset:34816
	ds_read_b128 v[160:163], v207 offset:35840
	ds_read_b128 v[164:167], v207 offset:36864
	ds_read_b128 v[168:171], v207 offset:37888
	ds_read_b128 v[186:189], v207 offset:38912
	ds_read_b128 v[190:193], v207 offset:39936
	global_load_lds_dwordx4 v180, s[14:15]
	s_mov_b32 m0, s25
	s_nop 0
	global_load_lds_dwordx4 v176, s[14:15]
	s_add_i32 s14, 0, 0x1c000
	v_add_u32_e32 v2, s14, v1
	ds_read_b128 v[194:197], v2
	ds_read_b128 v[198:201], v2 offset:1024
	ds_read_b128 v[202:205], v2 offset:2048
	ds_read_b128 v[208:211], v2 offset:3072
	s_waitcnt lgkmcnt(0)
	s_barrier
	s_setprio 1
	v_mfma_f32_16x16x32_bf16 v[68:71], v[132:135], v[148:151], v[68:71]
	v_mfma_f32_16x16x32_bf16 v[72:75], v[140:143], v[148:151], v[72:75]
	v_mfma_f32_16x16x32_bf16 v[120:123], v[132:135], v[156:159], v[120:123]
	v_mfma_f32_16x16x32_bf16 v[116:119], v[140:143], v[156:159], v[116:119]
	v_mfma_f32_16x16x32_bf16 v[112:115], v[132:135], v[164:167], v[112:115]
	v_mfma_f32_16x16x32_bf16 v[108:111], v[140:143], v[164:167], v[108:111]
	v_mfma_f32_16x16x32_bf16 v[104:107], v[132:135], v[186:189], v[104:107]
	v_mfma_f32_16x16x32_bf16 v[100:103], v[140:143], v[186:189], v[100:103]
	v_mfma_f32_16x16x32_bf16 v[68:71], v[136:139], v[152:155], v[68:71]
	v_mfma_f32_16x16x32_bf16 v[72:75], v[144:147], v[152:155], v[72:75]
	v_mfma_f32_16x16x32_bf16 v[120:123], v[136:139], v[160:163], v[120:123]
	v_mfma_f32_16x16x32_bf16 v[116:119], v[144:147], v[160:163], v[116:119]
	v_mfma_f32_16x16x32_bf16 v[112:115], v[136:139], v[168:171], v[112:115]
	v_mfma_f32_16x16x32_bf16 v[108:111], v[144:147], v[168:171], v[108:111]
	v_mfma_f32_16x16x32_bf16 v[104:107], v[136:139], v[190:193], v[104:107]
	v_mfma_f32_16x16x32_bf16 v[100:103], v[144:147], v[190:193], v[100:103]
	v_mfma_f32_16x16x32_bf16 v[76:79], v[194:197], v[148:151], v[76:79]
	v_mfma_f32_16x16x32_bf16 v[80:83], v[202:205], v[148:151], v[80:83]
	v_mfma_f32_16x16x32_bf16 v[96:99], v[194:197], v[156:159], v[96:99]
	v_mfma_f32_16x16x32_bf16 v[92:95], v[202:205], v[156:159], v[92:95]
	v_mfma_f32_16x16x32_bf16 v[88:91], v[194:197], v[164:167], v[88:91]
	v_mfma_f32_16x16x32_bf16 v[84:87], v[202:205], v[164:167], v[84:87]
	v_mfma_f32_16x16x32_bf16 v[128:131], v[194:197], v[186:189], v[128:131]
	v_mfma_f32_16x16x32_bf16 v[124:127], v[202:205], v[186:189], v[124:127]
	v_mfma_f32_16x16x32_bf16 v[76:79], v[198:201], v[152:155], v[76:79]
	v_mfma_f32_16x16x32_bf16 v[80:83], v[208:211], v[152:155], v[80:83]
	v_mfma_f32_16x16x32_bf16 v[96:99], v[198:201], v[160:163], v[96:99]
	v_mfma_f32_16x16x32_bf16 v[92:95], v[208:211], v[160:163], v[92:95]
	v_mfma_f32_16x16x32_bf16 v[88:91], v[198:201], v[168:171], v[88:91]
	v_mfma_f32_16x16x32_bf16 v[84:87], v[208:211], v[168:171], v[84:87]
	v_mfma_f32_16x16x32_bf16 v[128:131], v[198:201], v[190:193], v[128:131]
	v_mfma_f32_16x16x32_bf16 v[124:127], v[208:211], v[190:193], v[124:127]
	s_setprio 0
	s_barrier
; #define LAS __attribute__((address_space(3)))
; __device__ __forceinline__ int opaque_tid() { int t = threadIdx.x; asm volatile("" : "+v"(t)); return t; }
; #define PG8_STAGE(bufoff, gbase, voff) do { _Pragma("unroll") for (int _i = 0; _i < 2; ++_i) \
;         __builtin_amdgcn_global_load_lds((const unsigned*)((const char*)(gbase) + (voff)[_i]), (LAS unsigned*)(lds + (bufoff) + ldsw + _i * 8192), 16, 0, 0); } while (0)
; #define PG8_LDA(dst, b, h) do { _Pragma("unroll") for (int m = 0; m < 4; ++m) _Pragma("unroll") for (int k = 0; k < 2; ++k) dst[m][k] = *(const LAS bf16x8*)(lds + PG8_SA(b, h) + aoff + m * 2048 + k * 1024); } while (0)
; #define PG8_MMA(ai, bj, At, Bt) do { __builtin_amdgcn_s_setprio(1); _Pragma("unroll") for (int m = 0; m < 4; ++m) _Pragma("unroll") for (int n = 0; n < 2; ++n) _Pragma("unroll") for (int k = 0; k < 2; ++k) \
;         acc[ai][bj][m][n] = __builtin_amdgcn_mfma_f32_16x16x32_bf16(Bt[n][k], At[m][k], acc[ai][bj][m][n], 0, 0, 0); __builtin_amdgcn_s_setprio(0); } while (0)
; #define PG8_WAIT_V(n) asm volatile("s_waitcnt vmcnt(" #n ")" ::: "memory")
;     __device__ __forceinline__ void operator()(f32x4 (&acc)[2][2][4][2], const Unit& u, int wr, int wc, int ui, int) const {
;         const int ol_ = opaque_tid() & 63, fr = ol_ & 15, fq = ol_ >> 4;
;         { float r_[2][4];
;           rs_read(r_, ui, wr, fr);
; #pragma unroll
;           for (int ai = 0; ai < 2; ++ai)
; #pragma unroll
;               for (int bj = 0; bj < 2; ++bj)
; #pragma unroll
;                   for (int m = 0; m < 4; ++m) { acc[ai][bj][m][0] *= r_[ai][m]; acc[ai][bj][m][1] *= r_[ai][m]; } }
;         const int col = u.pn * 128 + wc * 32 + 8 * fq;
;         if (fr >= 14) {
; #pragma unroll
;             for (int ai = 0; ai < 2; ++ai) { LAS f32x4* s = (LAS f32x4*)(hl + ((((ai * 2 + wr) * 4 + wc) * 8 + fq * 2 + (fr - 14)) * 32));
;                 s[0] = acc[ai][1][3][0]; s[1] = acc[ai][1][3][1]; }
; template <class Epi, class Sched>
; __device__ __forceinline__ void gemm_phase(LAS unsigned char* lds, const Gemm g, const Sched& S, const Epi& E) {
;     ...
;             PG8_LDA(At, 1, 1); PG8_STAGE(PG8_SA(1, 0), a3, voffA);
;             PG8_BAR; PG8_WAIT_L(0); PG8_MMA(1, 0, At, B0); PG8_BAR; PG8_SCHED;
;             PG8_STAGE(PG8_SB(1, 1), b3 + hstepB, voffB);
;             PG8_WAIT_V(6); PG8_BAR; PG8_MMA(1, 1, At, B1); PG8_BAR;
	ds_read_b128 v[148:151], v207 offset:49152
	ds_read_b128 v[152:155], v207 offset:50176
	ds_read_b128 v[156:159], v207 offset:51200
	ds_read_b128 v[160:163], v207 offset:52224
	ds_read_b128 v[164:167], v207 offset:53248
	ds_read_b128 v[168:171], v207 offset:54272
	ds_read_b128 v[186:189], v207 offset:55296
	ds_read_b128 v[190:193], v207 offset:56320
	s_add_i32 s15, s72, s19
	v_lshl_add_u64 v[172:173], v[172:173], 0, s[8:9]
	s_mov_b32 m0, s15
	s_nop 0
	global_load_lds_dwordx4 v[172:173], off
	v_lshl_add_u64 v[172:173], v[212:213], 0, s[8:9]
	s_add_i32 m0, s15, 0x2000
	s_nop 0
	global_load_lds_dwordx4 v[172:173], off
	s_mov_b32 m0, s30
	v_lshl_add_u64 v[172:173], v[216:217], 0, s[8:9]
	s_nop 0
	global_load_lds_dwordx4 v[172:173], off
	v_lshl_add_u64 v[172:173], v[218:219], 0, s[8:9]
	s_mov_b32 m0, s31
	s_nop 0
	global_load_lds_dwordx4 v[172:173], off
	s_add_u32 s6, s6, 0x80080
	s_addc_u32 s7, s7, 0
	s_add_i32 s14, s14, s19
	s_mov_b32 m0, s14
	s_nop 0
	global_load_lds_dwordx4 v178, s[6:7]
	s_add_i32 m0, s14, 0x2000
	s_nop 0
	global_load_lds_dwordx4 v174, s[6:7]
	s_waitcnt lgkmcnt(0)
	s_waitcnt vmcnt(6)
	s_barrier
	s_setprio 1
	v_mfma_f32_16x16x32_bf16 v[56:59], v[132:135], v[148:151], v[56:59]
	v_mfma_f32_16x16x32_bf16 v[52:55], v[140:143], v[148:151], v[52:55]
	v_mfma_f32_16x16x32_bf16 v[48:51], v[132:135], v[156:159], v[48:51]
	v_mfma_f32_16x16x32_bf16 v[44:47], v[140:143], v[156:159], v[44:47]
	v_mfma_f32_16x16x32_bf16 v[40:43], v[132:135], v[164:167], v[40:43]
	v_mfma_f32_16x16x32_bf16 v[36:39], v[140:143], v[164:167], v[36:39]
	v_mfma_f32_16x16x32_bf16 v[32:35], v[132:135], v[186:189], v[32:35]
	v_mfma_f32_16x16x32_bf16 v[28:31], v[140:143], v[186:189], v[28:31]
	v_mfma_f32_16x16x32_bf16 v[56:59], v[136:139], v[152:155], v[56:59]
	v_mfma_f32_16x16x32_bf16 v[52:55], v[144:147], v[152:155], v[52:55]
	v_mfma_f32_16x16x32_bf16 v[48:51], v[136:139], v[160:163], v[48:51]
	v_mfma_f32_16x16x32_bf16 v[44:47], v[144:147], v[160:163], v[44:47]
	v_mfma_f32_16x16x32_bf16 v[40:43], v[136:139], v[168:171], v[40:43]
	v_mfma_f32_16x16x32_bf16 v[36:39], v[144:147], v[168:171], v[36:39]
	v_mfma_f32_16x16x32_bf16 v[32:35], v[136:139], v[190:193], v[32:35]
	v_mfma_f32_16x16x32_bf16 v[28:31], v[144:147], v[190:193], v[28:31]
	v_mfma_f32_16x16x32_bf16 v[24:27], v[194:197], v[148:151], v[24:27]
	v_mfma_f32_16x16x32_bf16 v[20:23], v[202:205], v[148:151], v[20:23]
	v_mfma_f32_16x16x32_bf16 v[16:19], v[194:197], v[156:159], v[16:19]
	v_mfma_f32_16x16x32_bf16 v[12:15], v[202:205], v[156:159], v[12:15]
	v_mfma_f32_16x16x32_bf16 v[8:11], v[194:197], v[164:167], v[8:11]
	v_mfma_f32_16x16x32_bf16 v[4:7], v[202:205], v[164:167], v[4:7]
	v_mfma_f32_16x16x32_bf16 v[60:63], v[194:197], v[186:189], v[60:63]
	v_mfma_f32_16x16x32_bf16 v[64:67], v[202:205], v[186:189], v[64:67]
	v_mfma_f32_16x16x32_bf16 v[24:27], v[198:201], v[152:155], v[24:27]
	v_mfma_f32_16x16x32_bf16 v[20:23], v[208:211], v[152:155], v[20:23]
	v_mfma_f32_16x16x32_bf16 v[16:19], v[198:201], v[160:163], v[16:19]
	v_mfma_f32_16x16x32_bf16 v[12:15], v[208:211], v[160:163], v[12:15]
	v_mfma_f32_16x16x32_bf16 v[8:11], v[198:201], v[168:171], v[8:11]
	v_mfma_f32_16x16x32_bf16 v[4:7], v[208:211], v[168:171], v[4:7]
	v_mfma_f32_16x16x32_bf16 v[60:63], v[198:201], v[190:193], v[60:63]
	v_mfma_f32_16x16x32_bf16 v[64:67], v[208:211], v[190:193], v[64:67]
	s_setprio 0
	s_add_i32 s71, s71, 2
	s_add_u32 s4, s4, 0x100
	s_addc_u32 s5, s5, 0
	s_add_u32 s69, s69, 0x100
	s_addc_u32 s70, s70, 0
	s_cmp_gt_u32 s71, 29
	s_barrier
	s_cbranch_scc0 .LBB0_1526
	s_lshl_b32 s4, s66, 10
	v_mov_b32_e32 v134, v0
	s_and_b32 s4, s4, 0x400
	s_add_i32 s4, s35, s4
	v_and_b32_e32 v210, 15, v134
	v_lshl_add_u32 v2, v210, 2, s4
	ds_read2_b32 v[204:205], v2 offset1:16
	ds_read2_b32 v[202:203], v2 offset0:32 offset1:48
	ds_read2_b32 v[198:199], v2 offset0:128 offset1:144
	ds_read2_b32 v[196:197], v2 offset0:160 offset1:176
	v_cmp_lt_u32_e32 vcc, 13, v210
	s_waitcnt lgkmcnt(0)
	v_mov_b32_e32 v206, v205
	v_mov_b32_e32 v208, v203
	v_mov_b32_e32 v2, v199
	v_mov_b32_e32 v200, v197
	v_pk_mul_f32 v[132:133], v[130:131], v[208:209] op_sel_hi:[1,0]
	v_pk_mul_f32 v[130:131], v[128:129], v[208:209] op_sel_hi:[1,0]
	v_pk_mul_f32 v[128:129], v[126:127], v[208:209] op_sel_hi:[1,0]
	v_pk_mul_f32 v[126:127], v[124:125], v[208:209] op_sel_hi:[1,0]
	v_pk_mul_f32 v[62:63], v[62:63], v[200:201] op_sel_hi:[1,0]
	v_pk_mul_f32 v[60:61], v[60:61], v[200:201] op_sel_hi:[1,0]
	v_pk_mul_f32 v[66:67], v[66:67], v[200:201] op_sel_hi:[1,0]
	v_pk_mul_f32 v[64:65], v[64:65], v[200:201] op_sel_hi:[1,0]
	v_bfe_u32 v125, v134, 4, 2
	s_and_saveexec_b64 s[4:5], vcc
	s_cbranch_execz .LBB0_1529
	v_lshlrev_b32_e32 v124, 1, v125
	v_add3_u32 v124, v210, v124, -14
	v_add_u32_e32 v134, s39, v124
	v_add_u32_e32 v124, s38, v124
	v_lshl_add_u32 v124, v124, 5, s62
	v_lshl_add_u32 v134, v134, 5, s62
	ds_write_b128 v124, v[130:133]
	ds_write_b128 v124, v[126:129] offset:16
	ds_write_b128 v134, v[60:63]
	ds_write_b128 v134, v[64:67] offset:16
